# LayerNorm items: four rows in flight per wave (was three), counted vmcnt up to 48
# speedup vs baseline: 1.0089x; 1.0089x over previous
; DI void ln_finish(const Params& p, float* __restrict__ pr, const float4 (&v)[8], int lane) {
;   float s = 0.f;
; #pragma unroll
;   for (int i = 0; i < 8; ++i) s += v[i].x + v[i].y + v[i].z + v[i].w;
; #pragma unroll
;   for (int o = 32; o >= 1; o >>= 1) s += __shfl_xor(s, o);
;   const float mu = s * (1.f / 2048.f);
;   float q = 0.f;
; #pragma unroll
;   for (int i = 0; i < 8; ++i) {
;     const float a = v[i].x - mu, b = v[i].y - mu, c = v[i].z - mu, d = v[i].w - mu;
;     q += a * a + b * b + c * c + d * d;
;   }
; #pragma unroll
;   for (int o = 32; o >= 1; o >>= 1) q += __shfl_xor(q, o);
;   const float rstd = rsqrtf(q * (1.f / 2048.f) + EPSV);
; __device__ void phaseD_handoff(const Params& p, unsigned char* smem) {
;     ...
;     const int row0 = panel * 256 + chunk * 64 + w * 8;
; #pragma unroll 1
;     for (int k = 0; k < 4; ++k) {
;       float* pa = p.out + O_Y + (size_t)(row0 + k) * 2048;
;       float* pb = p.out + O_Y + (size_t)(row0 + 4 + k) * 2048;
;       float4 va[8], vb[8];
; #pragma unroll
;       for (int i = 0; i < 8; ++i) va[i] = *reinterpret_cast<const float4*>(pa + (i * 64 + lane) * 4);
.LBB0_670:
	s_lshl_b32 s4, s4, 8
	s_lshl_b32 s5, s6, 6
	s_and_b32 s5, s5, 0xc0
	s_add_i32 s4, s10, s4
	s_add_i32 s4, s4, s5
	s_ashr_i32 s5, s4, 31
	s_lshl_b64 s[4:5], s[4:5], 13
	v_lshl_add_u64 v[100:101], v[86:87], 0, s[4:5]
	s_barrier
	s_mov_b32 s24, 0x0
	s_mov_b32 s25, 0
	v_lshl_add_u64 v[88:89], v[100:101], 0, s[24:25]
	s_mov_b32 s24, 0x1000
	v_lshl_add_u64 v[90:91], v[100:101], 0, s[24:25]
	global_load_dwordx4 v[0:3], v[88:89], off
	global_load_dwordx4 v[4:7], v[88:89], off offset:1024
	global_load_dwordx4 v[8:11], v[88:89], off offset:2048
	global_load_dwordx4 v[12:15], v[88:89], off offset:3072
	global_load_dwordx4 v[16:19], v[90:91], off
	global_load_dwordx4 v[20:23], v[90:91], off offset:1024
	global_load_dwordx4 v[24:27], v[90:91], off offset:2048
	global_load_dwordx4 v[28:31], v[90:91], off offset:3072
	s_mov_b32 s24, 0x2000
	s_mov_b32 s25, 0
	v_lshl_add_u64 v[92:93], v[100:101], 0, s[24:25]
	s_mov_b32 s24, 0x3000
	v_lshl_add_u64 v[94:95], v[100:101], 0, s[24:25]
	global_load_dwordx4 v[32:35], v[92:93], off
	global_load_dwordx4 v[36:39], v[92:93], off offset:1024
	global_load_dwordx4 v[40:43], v[92:93], off offset:2048
	global_load_dwordx4 v[44:47], v[92:93], off offset:3072
	global_load_dwordx4 v[48:51], v[94:95], off
	global_load_dwordx4 v[52:55], v[94:95], off offset:1024
	global_load_dwordx4 v[56:59], v[94:95], off offset:2048
	global_load_dwordx4 v[60:63], v[94:95], off offset:3072
	s_mov_b32 s24, 0x4000
	s_mov_b32 s25, 0
	v_lshl_add_u64 v[96:97], v[100:101], 0, s[24:25]
	s_mov_b32 s24, 0x5000
	v_lshl_add_u64 v[98:99], v[100:101], 0, s[24:25]
	global_load_dwordx4 v[176:179], v[96:97], off
	global_load_dwordx4 v[180:183], v[96:97], off offset:1024
	global_load_dwordx4 v[184:187], v[96:97], off offset:2048
	global_load_dwordx4 v[188:191], v[96:97], off offset:3072
	global_load_dwordx4 v[192:195], v[98:99], off
	global_load_dwordx4 v[196:199], v[98:99], off offset:1024
	global_load_dwordx4 v[200:203], v[98:99], off offset:2048
	global_load_dwordx4 v[204:207], v[98:99], off offset:3072
	s_mov_b32 s24, 0x6000
	s_mov_b32 s25, 0
	v_lshl_add_u64 v[246:247], v[100:101], 0, s[24:25]
	s_mov_b32 s24, 0x7000
	v_lshl_add_u64 v[248:249], v[100:101], 0, s[24:25]
	global_load_dwordx4 v[214:217], v[246:247], off
	global_load_dwordx4 v[218:221], v[246:247], off offset:1024
	global_load_dwordx4 v[222:225], v[246:247], off offset:2048
	global_load_dwordx4 v[226:229], v[246:247], off offset:3072
	global_load_dwordx4 v[230:233], v[248:249], off
	global_load_dwordx4 v[234:237], v[248:249], off offset:1024
	global_load_dwordx4 v[238:241], v[248:249], off offset:2048
	global_load_dwordx4 v[242:245], v[248:249], off offset:3072
	s_waitcnt vmcnt(24)
	v_add_f32_e32 v208, v0, v4
	v_add_f32_e32 v209, v1, v5
	v_add_f32_e32 v210, v2, v6
	v_add_f32_e32 v211, v3, v7
	v_add_f32_e32 v208, v8, v208
	v_add_f32_e32 v209, v9, v209
	v_add_f32_e32 v210, v10, v210
	v_add_f32_e32 v211, v11, v211
	v_add_f32_e32 v208, v12, v208
	v_add_f32_e32 v209, v13, v209
	v_add_f32_e32 v210, v14, v210
	v_add_f32_e32 v211, v15, v211
	v_add_f32_e32 v208, v16, v208
	v_add_f32_e32 v209, v17, v209
	v_add_f32_e32 v210, v18, v210
	v_add_f32_e32 v211, v19, v211
	v_add_f32_e32 v208, v20, v208
	v_add_f32_e32 v209, v21, v209
	v_add_f32_e32 v210, v22, v210
	v_add_f32_e32 v211, v23, v211
	v_add_f32_e32 v208, v24, v208
	v_add_f32_e32 v209, v25, v209
	v_add_f32_e32 v210, v26, v210
	v_add_f32_e32 v211, v27, v211
	v_add_f32_e32 v208, v28, v208
	v_add_f32_e32 v209, v29, v209
	v_add_f32_e32 v210, v30, v210
	v_add_f32_e32 v211, v31, v211
	v_add_f32_e32 v208, v208, v209
	v_add_f32_e32 v210, v210, v211
	v_add_f32_e32 v208, v208, v210
	s_nop 1
	v_add_f32_dpp v208, v208, v208 quad_perm:[1,0,3,2] row_mask:0xf bank_mask:0xf
	s_nop 1
	v_add_f32_dpp v208, v208, v208 quad_perm:[2,3,0,1] row_mask:0xf bank_mask:0xf
	s_nop 1
	v_add_f32_dpp v208, v208, v208 row_half_mirror row_mask:0xf bank_mask:0xf
	s_nop 1
	v_add_f32_dpp v208, v208, v208 row_mirror row_mask:0xf bank_mask:0xf
	s_nop 1
	v_readlane_b32 s16, v208, 0
	v_readlane_b32 s17, v208, 16
	v_readlane_b32 s18, v208, 32
	v_readlane_b32 s19, v208, 48
	s_nop 1
	v_mov_b32_e32 v208, s16
	v_add_f32_e32 v208, s17, v208
	v_add_f32_e32 v208, s18, v208
	v_add_f32_e32 v208, s19, v208
	v_mul_f32_e32 v212, 0x3a000000, v208
	v_sub_f32_e32 v0, v0, v212
	v_sub_f32_e32 v1, v1, v212
	v_sub_f32_e32 v2, v2, v212
	v_sub_f32_e32 v3, v3, v212
	v_sub_f32_e32 v4, v4, v212
	v_sub_f32_e32 v5, v5, v212
	v_sub_f32_e32 v6, v6, v212
	v_sub_f32_e32 v7, v7, v212
	v_sub_f32_e32 v8, v8, v212
	v_sub_f32_e32 v9, v9, v212
	v_sub_f32_e32 v10, v10, v212
	v_sub_f32_e32 v11, v11, v212
	v_sub_f32_e32 v12, v12, v212
	v_sub_f32_e32 v13, v13, v212
	v_sub_f32_e32 v14, v14, v212
	v_sub_f32_e32 v15, v15, v212
	v_sub_f32_e32 v16, v16, v212
	v_sub_f32_e32 v17, v17, v212
	v_sub_f32_e32 v18, v18, v212
	v_sub_f32_e32 v19, v19, v212
	v_sub_f32_e32 v20, v20, v212
	v_sub_f32_e32 v21, v21, v212
	v_sub_f32_e32 v22, v22, v212
	v_sub_f32_e32 v23, v23, v212
	v_sub_f32_e32 v24, v24, v212
	v_sub_f32_e32 v25, v25, v212
	v_sub_f32_e32 v26, v26, v212
	v_sub_f32_e32 v27, v27, v212
	v_sub_f32_e32 v28, v28, v212
	v_sub_f32_e32 v29, v29, v212
	v_sub_f32_e32 v30, v30, v212
	v_sub_f32_e32 v31, v31, v212
	v_mul_f32_e32 v208, v0, v0
	v_mul_f32_e32 v209, v1, v1
	v_mul_f32_e32 v210, v2, v2
	v_mul_f32_e32 v211, v3, v3
	v_fmac_f32_e32 v208, v4, v4
	v_fmac_f32_e32 v209, v5, v5
	v_fmac_f32_e32 v210, v6, v6
	v_fmac_f32_e32 v211, v7, v7
	v_fmac_f32_e32 v208, v8, v8
	v_fmac_f32_e32 v209, v9, v9
	v_fmac_f32_e32 v210, v10, v10
	v_fmac_f32_e32 v211, v11, v11
	v_fmac_f32_e32 v208, v12, v12
	v_fmac_f32_e32 v209, v13, v13
	v_fmac_f32_e32 v210, v14, v14
; DI void ln_finish(const Params& p, float* __restrict__ pr, const float4 (&v)[8], int lane) {
;   float s = 0.f;
; #pragma unroll
;   for (int i = 0; i < 8; ++i) s += v[i].x + v[i].y + v[i].z + v[i].w;
; #pragma unroll
;   for (int o = 32; o >= 1; o >>= 1) s += __shfl_xor(s, o);
;   const float mu = s * (1.f / 2048.f);
;   float q = 0.f;
; #pragma unroll
;   for (int i = 0; i < 8; ++i) {
;     const float a = v[i].x - mu, b = v[i].y - mu, c = v[i].z - mu, d = v[i].w - mu;
;     q += a * a + b * b + c * c + d * d;
;   }
; #pragma unroll
;   for (int o = 32; o >= 1; o >>= 1) q += __shfl_xor(q, o);
;   const float rstd = rsqrtf(q * (1.f / 2048.f) + EPSV);
; #pragma unroll
;   for (int i = 0; i < 8; ++i) {
;     const int c0 = (i * 64 + lane) * 4;
;     const float4 g = *reinterpret_cast<const float4*>(p.ln_g + c0);
;     const float4 bb = *reinterpret_cast<const float4*>(p.ln_b + c0);
;     float4 o;
;     o.x = (v[i].x - mu) * rstd * g.x + bb.x;
;     o.y = (v[i].y - mu) * rstd * g.y + bb.y;
;     o.z = (v[i].z - mu) * rstd * g.z + bb.z;
;     o.w = (v[i].w - mu) * rstd * g.w + bb.w;
;     *reinterpret_cast<float4*>(pr + c0) = o;
;   }
; }
; __device__ void phaseD_handoff(const Params& p, unsigned char* smem) {
;     ...
;       for (int i = 0; i < 8; ++i) va[i] = *reinterpret_cast<const float4*>(pa + (i * 64 + lane) * 4);
; #pragma unroll
;       for (int i = 0; i < 8; ++i) vb[i] = *reinterpret_cast<const float4*>(pb + (i * 64 + lane) * 4);
;       ln_finish(p, pa, va, lane);
	v_fmac_f32_e32 v211, v15, v15
	v_fmac_f32_e32 v208, v16, v16
	v_fmac_f32_e32 v209, v17, v17
	v_fmac_f32_e32 v210, v18, v18
	v_fmac_f32_e32 v211, v19, v19
	v_fmac_f32_e32 v208, v20, v20
	v_fmac_f32_e32 v209, v21, v21
	v_fmac_f32_e32 v210, v22, v22
	v_fmac_f32_e32 v211, v23, v23
	v_fmac_f32_e32 v208, v24, v24
	v_fmac_f32_e32 v209, v25, v25
	v_fmac_f32_e32 v210, v26, v26
	v_fmac_f32_e32 v211, v27, v27
	v_fmac_f32_e32 v208, v28, v28
	v_fmac_f32_e32 v209, v29, v29
	v_fmac_f32_e32 v210, v30, v30
	v_fmac_f32_e32 v211, v31, v31
	v_add_f32_e32 v208, v208, v209
	v_add_f32_e32 v210, v210, v211
	v_add_f32_e32 v208, v208, v210
	s_nop 1
	v_add_f32_dpp v208, v208, v208 quad_perm:[1,0,3,2] row_mask:0xf bank_mask:0xf
	s_nop 1
	v_add_f32_dpp v208, v208, v208 quad_perm:[2,3,0,1] row_mask:0xf bank_mask:0xf
	s_nop 1
	v_add_f32_dpp v208, v208, v208 row_half_mirror row_mask:0xf bank_mask:0xf
	s_nop 1
	v_add_f32_dpp v208, v208, v208 row_mirror row_mask:0xf bank_mask:0xf
	s_nop 1
	v_readlane_b32 s16, v208, 0
	v_readlane_b32 s17, v208, 16
	v_readlane_b32 s18, v208, 32
	v_readlane_b32 s19, v208, 48
	s_nop 1
	v_mov_b32_e32 v208, s16
	v_add_f32_e32 v208, s17, v208
	v_add_f32_e32 v208, s18, v208
	v_add_f32_e32 v208, s19, v208
	v_mov_b32_e32 v213, 0x3727c5ac
	v_fmac_f32_e32 v213, 0x3a000000, v208
	v_rsq_f32_e32 v213, v213
	s_nop 0
	v_mul_f32_e32 v0, v0, v213
	v_mul_f32_e32 v1, v1, v213
	v_mul_f32_e32 v2, v2, v213
	v_mul_f32_e32 v3, v3, v213
	v_mul_f32_e32 v4, v4, v213
	v_mul_f32_e32 v5, v5, v213
	v_mul_f32_e32 v6, v6, v213
	v_mul_f32_e32 v7, v7, v213
	v_mul_f32_e32 v8, v8, v213
	v_mul_f32_e32 v9, v9, v213
	v_mul_f32_e32 v10, v10, v213
	v_mul_f32_e32 v11, v11, v213
	v_mul_f32_e32 v12, v12, v213
	v_mul_f32_e32 v13, v13, v213
	v_mul_f32_e32 v14, v14, v213
	v_mul_f32_e32 v15, v15, v213
	v_mul_f32_e32 v16, v16, v213
	v_mul_f32_e32 v17, v17, v213
	v_mul_f32_e32 v18, v18, v213
	v_mul_f32_e32 v19, v19, v213
	v_mul_f32_e32 v20, v20, v213
	v_mul_f32_e32 v21, v21, v213
	v_mul_f32_e32 v22, v22, v213
	v_mul_f32_e32 v23, v23, v213
	v_mul_f32_e32 v24, v24, v213
	v_mul_f32_e32 v25, v25, v213
	v_mul_f32_e32 v26, v26, v213
	v_mul_f32_e32 v27, v27, v213
	v_mul_f32_e32 v28, v28, v213
	v_mul_f32_e32 v29, v29, v213
	v_mul_f32_e32 v30, v30, v213
	v_mul_f32_e32 v31, v31, v213
	v_fma_f32 v0, v0, v112, v144
	v_fma_f32 v1, v1, v113, v145
	v_fma_f32 v2, v2, v114, v146
	v_fma_f32 v3, v3, v115, v147
	v_fma_f32 v4, v4, v116, v148
	v_fma_f32 v5, v5, v117, v149
	v_fma_f32 v6, v6, v118, v150
	v_fma_f32 v7, v7, v119, v151
	v_fma_f32 v8, v8, v120, v152
	v_fma_f32 v9, v9, v121, v153
	v_fma_f32 v10, v10, v122, v154
	v_fma_f32 v11, v11, v123, v155
	v_fma_f32 v12, v12, v124, v156
	v_fma_f32 v13, v13, v125, v157
	v_fma_f32 v14, v14, v126, v158
	v_fma_f32 v15, v15, v127, v159
	v_fma_f32 v16, v16, v128, v160
	v_fma_f32 v17, v17, v129, v161
	v_fma_f32 v18, v18, v130, v162
	v_fma_f32 v19, v19, v131, v163
	v_fma_f32 v20, v20, v132, v164
	v_fma_f32 v21, v21, v133, v165
	v_fma_f32 v22, v22, v134, v166
	v_fma_f32 v23, v23, v135, v167
	v_fma_f32 v24, v24, v136, v168
	v_fma_f32 v25, v25, v137, v169
	v_fma_f32 v26, v26, v138, v170
	v_fma_f32 v27, v27, v139, v171
	v_fma_f32 v28, v28, v140, v172
	v_fma_f32 v29, v29, v141, v173
	v_fma_f32 v30, v30, v142, v174
	v_fma_f32 v31, v31, v143, v175
	global_store_dwordx4 v[88:89], v[0:3], off
	global_store_dwordx4 v[88:89], v[4:7], off offset:1024
	global_store_dwordx4 v[88:89], v[8:11], off offset:2048
	global_store_dwordx4 v[88:89], v[12:15], off offset:3072
	global_store_dwordx4 v[90:91], v[16:19], off
	global_store_dwordx4 v[90:91], v[20:23], off offset:1024
	global_store_dwordx4 v[90:91], v[24:27], off offset:2048
	global_store_dwordx4 v[90:91], v[28:31], off offset:3072
	s_mov_b32 s24, 0x8000
	s_mov_b32 s25, 0
	v_lshl_add_u64 v[88:89], v[100:101], 0, s[24:25]
	s_mov_b32 s24, 0x9000
	v_lshl_add_u64 v[90:91], v[100:101], 0, s[24:25]
	global_load_dwordx4 v[0:3], v[88:89], off
	global_load_dwordx4 v[4:7], v[88:89], off offset:1024
	global_load_dwordx4 v[8:11], v[88:89], off offset:2048
	global_load_dwordx4 v[12:15], v[88:89], off offset:3072
	global_load_dwordx4 v[16:19], v[90:91], off
	global_load_dwordx4 v[20:23], v[90:91], off offset:1024
	global_load_dwordx4 v[24:27], v[90:91], off offset:2048
	global_load_dwordx4 v[28:31], v[90:91], off offset:3072
	s_waitcnt vmcnt(32)
; DI void ln_finish(const Params& p, float* __restrict__ pr, const float4 (&v)[8], int lane) {
;   float s = 0.f;
; #pragma unroll
;   for (int i = 0; i < 8; ++i) s += v[i].x + v[i].y + v[i].z + v[i].w;
; #pragma unroll
;   for (int o = 32; o >= 1; o >>= 1) s += __shfl_xor(s, o);
;   const float mu = s * (1.f / 2048.f);
;   float q = 0.f;
; #pragma unroll
;   for (int i = 0; i < 8; ++i) {
;     const float a = v[i].x - mu, b = v[i].y - mu, c = v[i].z - mu, d = v[i].w - mu;
;     q += a * a + b * b + c * c + d * d;
;   }
; #pragma unroll
;   for (int o = 32; o >= 1; o >>= 1) q += __shfl_xor(q, o);
;   const float rstd = rsqrtf(q * (1.f / 2048.f) + EPSV);
; #pragma unroll
;   for (int i = 0; i < 8; ++i) {
;     const int c0 = (i * 64 + lane) * 4;
;     const float4 g = *reinterpret_cast<const float4*>(p.ln_g + c0);
;     const float4 bb = *reinterpret_cast<const float4*>(p.ln_b + c0);
;     float4 o;
;     o.x = (v[i].x - mu) * rstd * g.x + bb.x;
;     o.y = (v[i].y - mu) * rstd * g.y + bb.y;
;     o.z = (v[i].z - mu) * rstd * g.z + bb.z;
;     o.w = (v[i].w - mu) * rstd * g.w + bb.w;
	v_add_f32_e32 v208, v32, v36
	v_add_f32_e32 v209, v33, v37
	v_add_f32_e32 v210, v34, v38
	v_add_f32_e32 v211, v35, v39
	v_add_f32_e32 v208, v40, v208
	v_add_f32_e32 v209, v41, v209
	v_add_f32_e32 v210, v42, v210
	v_add_f32_e32 v211, v43, v211
	v_add_f32_e32 v208, v44, v208
	v_add_f32_e32 v209, v45, v209
	v_add_f32_e32 v210, v46, v210
	v_add_f32_e32 v211, v47, v211
	v_add_f32_e32 v208, v48, v208
	v_add_f32_e32 v209, v49, v209
	v_add_f32_e32 v210, v50, v210
	v_add_f32_e32 v211, v51, v211
	v_add_f32_e32 v208, v52, v208
	v_add_f32_e32 v209, v53, v209
	v_add_f32_e32 v210, v54, v210
	v_add_f32_e32 v211, v55, v211
	v_add_f32_e32 v208, v56, v208
	v_add_f32_e32 v209, v57, v209
	v_add_f32_e32 v210, v58, v210
	v_add_f32_e32 v211, v59, v211
	v_add_f32_e32 v208, v60, v208
	v_add_f32_e32 v209, v61, v209
	v_add_f32_e32 v210, v62, v210
	v_add_f32_e32 v211, v63, v211
	v_add_f32_e32 v208, v208, v209
	v_add_f32_e32 v210, v210, v211
	v_add_f32_e32 v208, v208, v210
	s_nop 1
	v_add_f32_dpp v208, v208, v208 quad_perm:[1,0,3,2] row_mask:0xf bank_mask:0xf
	s_nop 1
	v_add_f32_dpp v208, v208, v208 quad_perm:[2,3,0,1] row_mask:0xf bank_mask:0xf
	s_nop 1
	v_add_f32_dpp v208, v208, v208 row_half_mirror row_mask:0xf bank_mask:0xf
	s_nop 1
	v_add_f32_dpp v208, v208, v208 row_mirror row_mask:0xf bank_mask:0xf
	s_nop 1
	v_readlane_b32 s16, v208, 0
	v_readlane_b32 s17, v208, 16
	v_readlane_b32 s18, v208, 32
	v_readlane_b32 s19, v208, 48
	s_nop 1
	v_mov_b32_e32 v208, s16
	v_add_f32_e32 v208, s17, v208
	v_add_f32_e32 v208, s18, v208
	v_add_f32_e32 v208, s19, v208
	v_mul_f32_e32 v212, 0x3a000000, v208
	v_sub_f32_e32 v32, v32, v212
	v_sub_f32_e32 v33, v33, v212
	v_sub_f32_e32 v34, v34, v212
	v_sub_f32_e32 v35, v35, v212
	v_sub_f32_e32 v36, v36, v212
	v_sub_f32_e32 v37, v37, v212
	v_sub_f32_e32 v38, v38, v212
	v_sub_f32_e32 v39, v39, v212
	v_sub_f32_e32 v40, v40, v212
	v_sub_f32_e32 v41, v41, v212
	v_sub_f32_e32 v42, v42, v212
	v_sub_f32_e32 v43, v43, v212
	v_sub_f32_e32 v44, v44, v212
	v_sub_f32_e32 v45, v45, v212
	v_sub_f32_e32 v46, v46, v212
	v_sub_f32_e32 v47, v47, v212
	v_sub_f32_e32 v48, v48, v212
	v_sub_f32_e32 v49, v49, v212
	v_sub_f32_e32 v50, v50, v212
	v_sub_f32_e32 v51, v51, v212
	v_sub_f32_e32 v52, v52, v212
	v_sub_f32_e32 v53, v53, v212
	v_sub_f32_e32 v54, v54, v212
	v_sub_f32_e32 v55, v55, v212
	v_sub_f32_e32 v56, v56, v212
	v_sub_f32_e32 v57, v57, v212
	v_sub_f32_e32 v58, v58, v212
	v_sub_f32_e32 v59, v59, v212
	v_sub_f32_e32 v60, v60, v212
	v_sub_f32_e32 v61, v61, v212
	v_sub_f32_e32 v62, v62, v212
	v_sub_f32_e32 v63, v63, v212
	v_mul_f32_e32 v208, v32, v32
	v_mul_f32_e32 v209, v33, v33
	v_mul_f32_e32 v210, v34, v34
	v_mul_f32_e32 v211, v35, v35
	v_fmac_f32_e32 v208, v36, v36
	v_fmac_f32_e32 v209, v37, v37
	v_fmac_f32_e32 v210, v38, v38
	v_fmac_f32_e32 v211, v39, v39
	v_fmac_f32_e32 v208, v40, v40
	v_fmac_f32_e32 v209, v41, v41
	v_fmac_f32_e32 v210, v42, v42
	v_fmac_f32_e32 v211, v43, v43
	v_fmac_f32_e32 v208, v44, v44
	v_fmac_f32_e32 v209, v45, v45
	v_fmac_f32_e32 v210, v46, v46
	v_fmac_f32_e32 v211, v47, v47
	v_fmac_f32_e32 v208, v48, v48
	v_fmac_f32_e32 v209, v49, v49
	v_fmac_f32_e32 v210, v50, v50
	v_fmac_f32_e32 v211, v51, v51
	v_fmac_f32_e32 v208, v52, v52
	v_fmac_f32_e32 v209, v53, v53
	v_fmac_f32_e32 v210, v54, v54
	v_fmac_f32_e32 v211, v55, v55
	v_fmac_f32_e32 v208, v56, v56
	v_fmac_f32_e32 v209, v57, v57
	v_fmac_f32_e32 v210, v58, v58
	v_fmac_f32_e32 v211, v59, v59
	v_fmac_f32_e32 v208, v60, v60
	v_fmac_f32_e32 v209, v61, v61
	v_fmac_f32_e32 v210, v62, v62
	v_fmac_f32_e32 v211, v63, v63
	v_add_f32_e32 v208, v208, v209
	v_add_f32_e32 v210, v210, v211
	v_add_f32_e32 v208, v208, v210
	s_nop 1
	v_add_f32_dpp v208, v208, v208 quad_perm:[1,0,3,2] row_mask:0xf bank_mask:0xf
	s_nop 1
	v_add_f32_dpp v208, v208, v208 quad_perm:[2,3,0,1] row_mask:0xf bank_mask:0xf
	s_nop 1
	v_add_f32_dpp v208, v208, v208 row_half_mirror row_mask:0xf bank_mask:0xf
	s_nop 1
	v_add_f32_dpp v208, v208, v208 row_mirror row_mask:0xf bank_mask:0xf
	s_nop 1
	v_readlane_b32 s16, v208, 0
	v_readlane_b32 s17, v208, 16
	v_readlane_b32 s18, v208, 32
	v_readlane_b32 s19, v208, 48
	s_nop 1
	v_mov_b32_e32 v208, s16
	v_add_f32_e32 v208, s17, v208
	v_add_f32_e32 v208, s18, v208
	v_add_f32_e32 v208, s19, v208
	v_mov_b32_e32 v213, 0x3727c5ac
	v_fmac_f32_e32 v213, 0x3a000000, v208
	v_rsq_f32_e32 v213, v213
	s_nop 0
	v_mul_f32_e32 v32, v32, v213
	v_mul_f32_e32 v33, v33, v213
	v_mul_f32_e32 v34, v34, v213
	v_mul_f32_e32 v35, v35, v213
	v_mul_f32_e32 v36, v36, v213
	v_mul_f32_e32 v37, v37, v213
	v_mul_f32_e32 v38, v38, v213
	v_mul_f32_e32 v39, v39, v213
	v_mul_f32_e32 v40, v40, v213
	v_mul_f32_e32 v41, v41, v213
	v_mul_f32_e32 v42, v42, v213
	v_mul_f32_e32 v43, v43, v213
	v_mul_f32_e32 v44, v44, v213
	v_mul_f32_e32 v45, v45, v213
	v_mul_f32_e32 v46, v46, v213
	v_mul_f32_e32 v47, v47, v213
	v_mul_f32_e32 v48, v48, v213
	v_mul_f32_e32 v49, v49, v213
	v_mul_f32_e32 v50, v50, v213
	v_mul_f32_e32 v51, v51, v213
	v_mul_f32_e32 v52, v52, v213
	v_mul_f32_e32 v53, v53, v213
	v_mul_f32_e32 v54, v54, v213
	v_mul_f32_e32 v55, v55, v213
	v_mul_f32_e32 v56, v56, v213
	v_mul_f32_e32 v57, v57, v213
	v_mul_f32_e32 v58, v58, v213
	v_mul_f32_e32 v59, v59, v213
	v_mul_f32_e32 v60, v60, v213
	v_mul_f32_e32 v61, v61, v213
	v_mul_f32_e32 v62, v62, v213
	v_mul_f32_e32 v63, v63, v213
	v_fma_f32 v32, v32, v112, v144
	v_fma_f32 v33, v33, v113, v145
	v_fma_f32 v34, v34, v114, v146
	v_fma_f32 v35, v35, v115, v147
	v_fma_f32 v36, v36, v116, v148
	v_fma_f32 v37, v37, v117, v149
	v_fma_f32 v38, v38, v118, v150
	v_fma_f32 v39, v39, v119, v151
	v_fma_f32 v40, v40, v120, v152
	v_fma_f32 v41, v41, v121, v153
	v_fma_f32 v42, v42, v122, v154
; DI void ln_finish(const Params& p, float* __restrict__ pr, const float4 (&v)[8], int lane) {
;     ...
;     o.x = (v[i].x - mu) * rstd * g.x + bb.x;
;     o.y = (v[i].y - mu) * rstd * g.y + bb.y;
;     o.z = (v[i].z - mu) * rstd * g.z + bb.z;
;     o.w = (v[i].w - mu) * rstd * g.w + bb.w;
;     *reinterpret_cast<float4*>(pr + c0) = o;
; __device__ void phaseD_handoff(const Params& p, unsigned char* smem) {
;     ...
;       for (int i = 0; i < 8; ++i) va[i] = *reinterpret_cast<const float4*>(pa + (i * 64 + lane) * 4);
; #pragma unroll
;       for (int i = 0; i < 8; ++i) vb[i] = *reinterpret_cast<const float4*>(pb + (i * 64 + lane) * 4);
;       ln_finish(p, pa, va, lane);
	v_fma_f32 v43, v43, v123, v155
	v_fma_f32 v44, v44, v124, v156
	v_fma_f32 v45, v45, v125, v157
	v_fma_f32 v46, v46, v126, v158
	v_fma_f32 v47, v47, v127, v159
	v_fma_f32 v48, v48, v128, v160
	v_fma_f32 v49, v49, v129, v161
	v_fma_f32 v50, v50, v130, v162
	v_fma_f32 v51, v51, v131, v163
	v_fma_f32 v52, v52, v132, v164
	v_fma_f32 v53, v53, v133, v165
	v_fma_f32 v54, v54, v134, v166
	v_fma_f32 v55, v55, v135, v167
	v_fma_f32 v56, v56, v136, v168
	v_fma_f32 v57, v57, v137, v169
	v_fma_f32 v58, v58, v138, v170
	v_fma_f32 v59, v59, v139, v171
	v_fma_f32 v60, v60, v140, v172
	v_fma_f32 v61, v61, v141, v173
	v_fma_f32 v62, v62, v142, v174
	v_fma_f32 v63, v63, v143, v175
	global_store_dwordx4 v[92:93], v[32:35], off
	global_store_dwordx4 v[92:93], v[36:39], off offset:1024
	global_store_dwordx4 v[92:93], v[40:43], off offset:2048
	global_store_dwordx4 v[92:93], v[44:47], off offset:3072
	global_store_dwordx4 v[94:95], v[48:51], off
	global_store_dwordx4 v[94:95], v[52:55], off offset:1024
	global_store_dwordx4 v[94:95], v[56:59], off offset:2048
	global_store_dwordx4 v[94:95], v[60:63], off offset:3072
	s_mov_b32 s24, 0xa000
	s_mov_b32 s25, 0
	v_lshl_add_u64 v[92:93], v[100:101], 0, s[24:25]
	s_mov_b32 s24, 0xb000
	v_lshl_add_u64 v[94:95], v[100:101], 0, s[24:25]
	global_load_dwordx4 v[32:35], v[92:93], off
	global_load_dwordx4 v[36:39], v[92:93], off offset:1024
	global_load_dwordx4 v[40:43], v[92:93], off offset:2048
	global_load_dwordx4 v[44:47], v[92:93], off offset:3072
	global_load_dwordx4 v[48:51], v[94:95], off
	global_load_dwordx4 v[52:55], v[94:95], off offset:1024
	global_load_dwordx4 v[56:59], v[94:95], off offset:2048
	global_load_dwordx4 v[60:63], v[94:95], off offset:3072
	s_waitcnt vmcnt(40)
	v_add_f32_e32 v208, v176, v180
	v_add_f32_e32 v209, v177, v181
	v_add_f32_e32 v210, v178, v182
	v_add_f32_e32 v211, v179, v183
	v_add_f32_e32 v208, v184, v208
	v_add_f32_e32 v209, v185, v209
	v_add_f32_e32 v210, v186, v210
	v_add_f32_e32 v211, v187, v211
	v_add_f32_e32 v208, v188, v208
	v_add_f32_e32 v209, v189, v209
	v_add_f32_e32 v210, v190, v210
	v_add_f32_e32 v211, v191, v211
	v_add_f32_e32 v208, v192, v208
	v_add_f32_e32 v209, v193, v209
	v_add_f32_e32 v210, v194, v210
	v_add_f32_e32 v211, v195, v211
	v_add_f32_e32 v208, v196, v208
	v_add_f32_e32 v209, v197, v209
	v_add_f32_e32 v210, v198, v210
	v_add_f32_e32 v211, v199, v211
	v_add_f32_e32 v208, v200, v208
	v_add_f32_e32 v209, v201, v209
	v_add_f32_e32 v210, v202, v210
	v_add_f32_e32 v211, v203, v211
	v_add_f32_e32 v208, v204, v208
	v_add_f32_e32 v209, v205, v209
	v_add_f32_e32 v210, v206, v210
	v_add_f32_e32 v211, v207, v211
	v_add_f32_e32 v208, v208, v209
	v_add_f32_e32 v210, v210, v211
	v_add_f32_e32 v208, v208, v210
	s_nop 1
	v_add_f32_dpp v208, v208, v208 quad_perm:[1,0,3,2] row_mask:0xf bank_mask:0xf
	s_nop 1
	v_add_f32_dpp v208, v208, v208 quad_perm:[2,3,0,1] row_mask:0xf bank_mask:0xf
	s_nop 1
	v_add_f32_dpp v208, v208, v208 row_half_mirror row_mask:0xf bank_mask:0xf
	s_nop 1
	v_add_f32_dpp v208, v208, v208 row_mirror row_mask:0xf bank_mask:0xf
	s_nop 1
	v_readlane_b32 s16, v208, 0
	v_readlane_b32 s17, v208, 16
	v_readlane_b32 s18, v208, 32
	v_readlane_b32 s19, v208, 48
	s_nop 1
	v_mov_b32_e32 v208, s16
	v_add_f32_e32 v208, s17, v208
	v_add_f32_e32 v208, s18, v208
	v_add_f32_e32 v208, s19, v208
	v_mul_f32_e32 v212, 0x3a000000, v208
	v_sub_f32_e32 v176, v176, v212
	v_sub_f32_e32 v177, v177, v212
	v_sub_f32_e32 v178, v178, v212
	v_sub_f32_e32 v179, v179, v212
	v_sub_f32_e32 v180, v180, v212
	v_sub_f32_e32 v181, v181, v212
	v_sub_f32_e32 v182, v182, v212
	v_sub_f32_e32 v183, v183, v212
	v_sub_f32_e32 v184, v184, v212
	v_sub_f32_e32 v185, v185, v212
	v_sub_f32_e32 v186, v186, v212
	v_sub_f32_e32 v187, v187, v212
	v_sub_f32_e32 v188, v188, v212
	v_sub_f32_e32 v189, v189, v212
	v_sub_f32_e32 v190, v190, v212
	v_sub_f32_e32 v191, v191, v212
	v_sub_f32_e32 v192, v192, v212
	v_sub_f32_e32 v193, v193, v212
	v_sub_f32_e32 v194, v194, v212
	v_sub_f32_e32 v195, v195, v212
	v_sub_f32_e32 v196, v196, v212
	v_sub_f32_e32 v197, v197, v212
	v_sub_f32_e32 v198, v198, v212
	v_sub_f32_e32 v199, v199, v212
	v_sub_f32_e32 v200, v200, v212
	v_sub_f32_e32 v201, v201, v212
	v_sub_f32_e32 v202, v202, v212
	v_sub_f32_e32 v203, v203, v212
	v_sub_f32_e32 v204, v204, v212
	v_sub_f32_e32 v205, v205, v212
	v_sub_f32_e32 v206, v206, v212
	v_sub_f32_e32 v207, v207, v212
	v_mul_f32_e32 v208, v176, v176
	v_mul_f32_e32 v209, v177, v177
	v_mul_f32_e32 v210, v178, v178
	v_mul_f32_e32 v211, v179, v179
	v_fmac_f32_e32 v208, v180, v180
	v_fmac_f32_e32 v209, v181, v181
	v_fmac_f32_e32 v210, v182, v182
	v_fmac_f32_e32 v211, v183, v183
	v_fmac_f32_e32 v208, v184, v184
	v_fmac_f32_e32 v209, v185, v185
	v_fmac_f32_e32 v210, v186, v186
	v_fmac_f32_e32 v211, v187, v187
	v_fmac_f32_e32 v208, v188, v188
	v_fmac_f32_e32 v209, v189, v189
	v_fmac_f32_e32 v210, v190, v190
	v_fmac_f32_e32 v211, v191, v191
	v_fmac_f32_e32 v208, v192, v192
	v_fmac_f32_e32 v209, v193, v193
	v_fmac_f32_e32 v210, v194, v194
	v_fmac_f32_e32 v211, v195, v195
	v_fmac_f32_e32 v208, v196, v196
	v_fmac_f32_e32 v209, v197, v197
	v_fmac_f32_e32 v210, v198, v198
	v_fmac_f32_e32 v211, v199, v199
	v_fmac_f32_e32 v208, v200, v200
	v_fmac_f32_e32 v209, v201, v201
	v_fmac_f32_e32 v210, v202, v202
	v_fmac_f32_e32 v211, v203, v203
	v_fmac_f32_e32 v208, v204, v204
	v_fmac_f32_e32 v209, v205, v205
	v_fmac_f32_e32 v210, v206, v206
	v_fmac_f32_e32 v211, v207, v207
	v_add_f32_e32 v208, v208, v209
	v_add_f32_e32 v210, v210, v211
	v_add_f32_e32 v208, v208, v210
	s_nop 1
	v_add_f32_dpp v208, v208, v208 quad_perm:[1,0,3,2] row_mask:0xf bank_mask:0xf
	s_nop 1
; DI void ln_finish(const Params& p, float* __restrict__ pr, const float4 (&v)[8], int lane) {
;   float s = 0.f;
; #pragma unroll
;   for (int i = 0; i < 8; ++i) s += v[i].x + v[i].y + v[i].z + v[i].w;
; #pragma unroll
;   for (int o = 32; o >= 1; o >>= 1) s += __shfl_xor(s, o);
;   const float mu = s * (1.f / 2048.f);
;   float q = 0.f;
; #pragma unroll
;   for (int i = 0; i < 8; ++i) {
;     const float a = v[i].x - mu, b = v[i].y - mu, c = v[i].z - mu, d = v[i].w - mu;
;     q += a * a + b * b + c * c + d * d;
;   }
; #pragma unroll
;   for (int o = 32; o >= 1; o >>= 1) q += __shfl_xor(q, o);
;   const float rstd = rsqrtf(q * (1.f / 2048.f) + EPSV);
; #pragma unroll
;   for (int i = 0; i < 8; ++i) {
;     const int c0 = (i * 64 + lane) * 4;
;     const float4 g = *reinterpret_cast<const float4*>(p.ln_g + c0);
;     const float4 bb = *reinterpret_cast<const float4*>(p.ln_b + c0);
;     float4 o;
;     o.x = (v[i].x - mu) * rstd * g.x + bb.x;
;     o.y = (v[i].y - mu) * rstd * g.y + bb.y;
;     o.z = (v[i].z - mu) * rstd * g.z + bb.z;
;     o.w = (v[i].w - mu) * rstd * g.w + bb.w;
;     *reinterpret_cast<float4*>(pr + c0) = o;
;   }
; }
	v_add_f32_dpp v208, v208, v208 quad_perm:[2,3,0,1] row_mask:0xf bank_mask:0xf
	s_nop 1
	v_add_f32_dpp v208, v208, v208 row_half_mirror row_mask:0xf bank_mask:0xf
	s_nop 1
	v_add_f32_dpp v208, v208, v208 row_mirror row_mask:0xf bank_mask:0xf
	s_nop 1
	v_readlane_b32 s16, v208, 0
	v_readlane_b32 s17, v208, 16
	v_readlane_b32 s18, v208, 32
	v_readlane_b32 s19, v208, 48
	s_nop 1
	v_mov_b32_e32 v208, s16
	v_add_f32_e32 v208, s17, v208
	v_add_f32_e32 v208, s18, v208
	v_add_f32_e32 v208, s19, v208
	v_mov_b32_e32 v213, 0x3727c5ac
	v_fmac_f32_e32 v213, 0x3a000000, v208
	v_rsq_f32_e32 v213, v213
	s_nop 0
	v_mul_f32_e32 v176, v176, v213
	v_mul_f32_e32 v177, v177, v213
	v_mul_f32_e32 v178, v178, v213
	v_mul_f32_e32 v179, v179, v213
	v_mul_f32_e32 v180, v180, v213
	v_mul_f32_e32 v181, v181, v213
	v_mul_f32_e32 v182, v182, v213
	v_mul_f32_e32 v183, v183, v213
	v_mul_f32_e32 v184, v184, v213
	v_mul_f32_e32 v185, v185, v213
	v_mul_f32_e32 v186, v186, v213
	v_mul_f32_e32 v187, v187, v213
	v_mul_f32_e32 v188, v188, v213
	v_mul_f32_e32 v189, v189, v213
	v_mul_f32_e32 v190, v190, v213
	v_mul_f32_e32 v191, v191, v213
	v_mul_f32_e32 v192, v192, v213
	v_mul_f32_e32 v193, v193, v213
	v_mul_f32_e32 v194, v194, v213
	v_mul_f32_e32 v195, v195, v213
	v_mul_f32_e32 v196, v196, v213
	v_mul_f32_e32 v197, v197, v213
	v_mul_f32_e32 v198, v198, v213
	v_mul_f32_e32 v199, v199, v213
	v_mul_f32_e32 v200, v200, v213
	v_mul_f32_e32 v201, v201, v213
	v_mul_f32_e32 v202, v202, v213
	v_mul_f32_e32 v203, v203, v213
	v_mul_f32_e32 v204, v204, v213
	v_mul_f32_e32 v205, v205, v213
	v_mul_f32_e32 v206, v206, v213
	v_mul_f32_e32 v207, v207, v213
	v_fma_f32 v176, v176, v112, v144
	v_fma_f32 v177, v177, v113, v145
	v_fma_f32 v178, v178, v114, v146
	v_fma_f32 v179, v179, v115, v147
	v_fma_f32 v180, v180, v116, v148
	v_fma_f32 v181, v181, v117, v149
	v_fma_f32 v182, v182, v118, v150
	v_fma_f32 v183, v183, v119, v151
	v_fma_f32 v184, v184, v120, v152
	v_fma_f32 v185, v185, v121, v153
	v_fma_f32 v186, v186, v122, v154
	v_fma_f32 v187, v187, v123, v155
	v_fma_f32 v188, v188, v124, v156
	v_fma_f32 v189, v189, v125, v157
	v_fma_f32 v190, v190, v126, v158
	v_fma_f32 v191, v191, v127, v159
	v_fma_f32 v192, v192, v128, v160
	v_fma_f32 v193, v193, v129, v161
	v_fma_f32 v194, v194, v130, v162
	v_fma_f32 v195, v195, v131, v163
	v_fma_f32 v196, v196, v132, v164
	v_fma_f32 v197, v197, v133, v165
	v_fma_f32 v198, v198, v134, v166
	v_fma_f32 v199, v199, v135, v167
	v_fma_f32 v200, v200, v136, v168
	v_fma_f32 v201, v201, v137, v169
	v_fma_f32 v202, v202, v138, v170
	v_fma_f32 v203, v203, v139, v171
	v_fma_f32 v204, v204, v140, v172
	v_fma_f32 v205, v205, v141, v173
	v_fma_f32 v206, v206, v142, v174
	v_fma_f32 v207, v207, v143, v175
	global_store_dwordx4 v[96:97], v[176:179], off
	global_store_dwordx4 v[96:97], v[180:183], off offset:1024
	global_store_dwordx4 v[96:97], v[184:187], off offset:2048
	global_store_dwordx4 v[96:97], v[188:191], off offset:3072
	global_store_dwordx4 v[98:99], v[192:195], off
	global_store_dwordx4 v[98:99], v[196:199], off offset:1024
	global_store_dwordx4 v[98:99], v[200:203], off offset:2048
	global_store_dwordx4 v[98:99], v[204:207], off offset:3072
	s_mov_b32 s24, 0xc000
	s_mov_b32 s25, 0
	v_lshl_add_u64 v[96:97], v[100:101], 0, s[24:25]
	s_mov_b32 s24, 0xd000
	v_lshl_add_u64 v[98:99], v[100:101], 0, s[24:25]
	global_load_dwordx4 v[176:179], v[96:97], off
	global_load_dwordx4 v[180:183], v[96:97], off offset:1024
	global_load_dwordx4 v[184:187], v[96:97], off offset:2048
	global_load_dwordx4 v[188:191], v[96:97], off offset:3072
	global_load_dwordx4 v[192:195], v[98:99], off
	global_load_dwordx4 v[196:199], v[98:99], off offset:1024
	global_load_dwordx4 v[200:203], v[98:99], off offset:2048
	global_load_dwordx4 v[204:207], v[98:99], off offset:3072
	s_waitcnt vmcnt(48)
	v_add_f32_e32 v208, v214, v218
	v_add_f32_e32 v209, v215, v219
	v_add_f32_e32 v210, v216, v220
	v_add_f32_e32 v211, v217, v221
	v_add_f32_e32 v208, v222, v208
	v_add_f32_e32 v209, v223, v209
	v_add_f32_e32 v210, v224, v210
	v_add_f32_e32 v211, v225, v211
	v_add_f32_e32 v208, v226, v208
	v_add_f32_e32 v209, v227, v209
	v_add_f32_e32 v210, v228, v210
	v_add_f32_e32 v211, v229, v211
	v_add_f32_e32 v208, v230, v208
	v_add_f32_e32 v209, v231, v209
	v_add_f32_e32 v210, v232, v210
	v_add_f32_e32 v211, v233, v211
	v_add_f32_e32 v208, v234, v208
	v_add_f32_e32 v209, v235, v209
	v_add_f32_e32 v210, v236, v210
	v_add_f32_e32 v211, v237, v211
	v_add_f32_e32 v208, v238, v208
	v_add_f32_e32 v209, v239, v209
	v_add_f32_e32 v210, v240, v210
	v_add_f32_e32 v211, v241, v211
	v_add_f32_e32 v208, v242, v208
	v_add_f32_e32 v209, v243, v209
	v_add_f32_e32 v210, v244, v210
	v_add_f32_e32 v211, v245, v211
	v_add_f32_e32 v208, v208, v209
	v_add_f32_e32 v210, v210, v211
	v_add_f32_e32 v208, v208, v210
	s_nop 1
	v_add_f32_dpp v208, v208, v208 quad_perm:[1,0,3,2] row_mask:0xf bank_mask:0xf
	s_nop 1
	v_add_f32_dpp v208, v208, v208 quad_perm:[2,3,0,1] row_mask:0xf bank_mask:0xf
	s_nop 1
	v_add_f32_dpp v208, v208, v208 row_half_mirror row_mask:0xf bank_mask:0xf
	s_nop 1
	v_add_f32_dpp v208, v208, v208 row_mirror row_mask:0xf bank_mask:0xf
	s_nop 1
	v_readlane_b32 s16, v208, 0
	v_readlane_b32 s17, v208, 16
	v_readlane_b32 s18, v208, 32
	v_readlane_b32 s19, v208, 48
	s_nop 1
	v_mov_b32_e32 v208, s16
	v_add_f32_e32 v208, s17, v208
	v_add_f32_e32 v208, s18, v208
	v_add_f32_e32 v208, s19, v208
	v_mul_f32_e32 v212, 0x3a000000, v208
	v_sub_f32_e32 v214, v214, v212
	v_sub_f32_e32 v215, v215, v212
	v_sub_f32_e32 v216, v216, v212
	v_sub_f32_e32 v217, v217, v212
	v_sub_f32_e32 v218, v218, v212
	v_sub_f32_e32 v219, v219, v212
	v_sub_f32_e32 v220, v220, v212
; DI void ln_finish(const Params& p, float* __restrict__ pr, const float4 (&v)[8], int lane) {
;   float s = 0.f;
; #pragma unroll
;   for (int i = 0; i < 8; ++i) s += v[i].x + v[i].y + v[i].z + v[i].w;
; #pragma unroll
;   for (int o = 32; o >= 1; o >>= 1) s += __shfl_xor(s, o);
;   const float mu = s * (1.f / 2048.f);
;   float q = 0.f;
; #pragma unroll
;   for (int i = 0; i < 8; ++i) {
;     const float a = v[i].x - mu, b = v[i].y - mu, c = v[i].z - mu, d = v[i].w - mu;
;     q += a * a + b * b + c * c + d * d;
;   }
; #pragma unroll
;   for (int o = 32; o >= 1; o >>= 1) q += __shfl_xor(q, o);
;   const float rstd = rsqrtf(q * (1.f / 2048.f) + EPSV);
; #pragma unroll
;   for (int i = 0; i < 8; ++i) {
;     const int c0 = (i * 64 + lane) * 4;
;     const float4 g = *reinterpret_cast<const float4*>(p.ln_g + c0);
;     const float4 bb = *reinterpret_cast<const float4*>(p.ln_b + c0);
;     float4 o;
;     o.x = (v[i].x - mu) * rstd * g.x + bb.x;
;     o.y = (v[i].y - mu) * rstd * g.y + bb.y;
;     o.z = (v[i].z - mu) * rstd * g.z + bb.z;
;     o.w = (v[i].w - mu) * rstd * g.w + bb.w;
;     *reinterpret_cast<float4*>(pr + c0) = o;
;   }
; }
	v_sub_f32_e32 v221, v221, v212
	v_sub_f32_e32 v222, v222, v212
	v_sub_f32_e32 v223, v223, v212
	v_sub_f32_e32 v224, v224, v212
	v_sub_f32_e32 v225, v225, v212
	v_sub_f32_e32 v226, v226, v212
	v_sub_f32_e32 v227, v227, v212
	v_sub_f32_e32 v228, v228, v212
	v_sub_f32_e32 v229, v229, v212
	v_sub_f32_e32 v230, v230, v212
	v_sub_f32_e32 v231, v231, v212
	v_sub_f32_e32 v232, v232, v212
	v_sub_f32_e32 v233, v233, v212
	v_sub_f32_e32 v234, v234, v212
	v_sub_f32_e32 v235, v235, v212
	v_sub_f32_e32 v236, v236, v212
	v_sub_f32_e32 v237, v237, v212
	v_sub_f32_e32 v238, v238, v212
	v_sub_f32_e32 v239, v239, v212
	v_sub_f32_e32 v240, v240, v212
	v_sub_f32_e32 v241, v241, v212
	v_sub_f32_e32 v242, v242, v212
	v_sub_f32_e32 v243, v243, v212
	v_sub_f32_e32 v244, v244, v212
	v_sub_f32_e32 v245, v245, v212
	v_mul_f32_e32 v208, v214, v214
	v_mul_f32_e32 v209, v215, v215
	v_mul_f32_e32 v210, v216, v216
	v_mul_f32_e32 v211, v217, v217
	v_fmac_f32_e32 v208, v218, v218
	v_fmac_f32_e32 v209, v219, v219
	v_fmac_f32_e32 v210, v220, v220
	v_fmac_f32_e32 v211, v221, v221
	v_fmac_f32_e32 v208, v222, v222
	v_fmac_f32_e32 v209, v223, v223
	v_fmac_f32_e32 v210, v224, v224
	v_fmac_f32_e32 v211, v225, v225
	v_fmac_f32_e32 v208, v226, v226
	v_fmac_f32_e32 v209, v227, v227
	v_fmac_f32_e32 v210, v228, v228
	v_fmac_f32_e32 v211, v229, v229
	v_fmac_f32_e32 v208, v230, v230
	v_fmac_f32_e32 v209, v231, v231
	v_fmac_f32_e32 v210, v232, v232
	v_fmac_f32_e32 v211, v233, v233
	v_fmac_f32_e32 v208, v234, v234
	v_fmac_f32_e32 v209, v235, v235
	v_fmac_f32_e32 v210, v236, v236
	v_fmac_f32_e32 v211, v237, v237
	v_fmac_f32_e32 v208, v238, v238
	v_fmac_f32_e32 v209, v239, v239
	v_fmac_f32_e32 v210, v240, v240
	v_fmac_f32_e32 v211, v241, v241
	v_fmac_f32_e32 v208, v242, v242
	v_fmac_f32_e32 v209, v243, v243
	v_fmac_f32_e32 v210, v244, v244
	v_fmac_f32_e32 v211, v245, v245
	v_add_f32_e32 v208, v208, v209
	v_add_f32_e32 v210, v210, v211
	v_add_f32_e32 v208, v208, v210
	s_nop 1
	v_add_f32_dpp v208, v208, v208 quad_perm:[1,0,3,2] row_mask:0xf bank_mask:0xf
	s_nop 1
	v_add_f32_dpp v208, v208, v208 quad_perm:[2,3,0,1] row_mask:0xf bank_mask:0xf
	s_nop 1
	v_add_f32_dpp v208, v208, v208 row_half_mirror row_mask:0xf bank_mask:0xf
	s_nop 1
	v_add_f32_dpp v208, v208, v208 row_mirror row_mask:0xf bank_mask:0xf
	s_nop 1
	v_readlane_b32 s16, v208, 0
	v_readlane_b32 s17, v208, 16
	v_readlane_b32 s18, v208, 32
	v_readlane_b32 s19, v208, 48
	s_nop 1
	v_mov_b32_e32 v208, s16
	v_add_f32_e32 v208, s17, v208
	v_add_f32_e32 v208, s18, v208
	v_add_f32_e32 v208, s19, v208
	v_mov_b32_e32 v213, 0x3727c5ac
	v_fmac_f32_e32 v213, 0x3a000000, v208
	v_rsq_f32_e32 v213, v213
	s_nop 0
	v_mul_f32_e32 v214, v214, v213
	v_mul_f32_e32 v215, v215, v213
	v_mul_f32_e32 v216, v216, v213
	v_mul_f32_e32 v217, v217, v213
	v_mul_f32_e32 v218, v218, v213
	v_mul_f32_e32 v219, v219, v213
	v_mul_f32_e32 v220, v220, v213
	v_mul_f32_e32 v221, v221, v213
	v_mul_f32_e32 v222, v222, v213
	v_mul_f32_e32 v223, v223, v213
	v_mul_f32_e32 v224, v224, v213
	v_mul_f32_e32 v225, v225, v213
	v_mul_f32_e32 v226, v226, v213
	v_mul_f32_e32 v227, v227, v213
	v_mul_f32_e32 v228, v228, v213
	v_mul_f32_e32 v229, v229, v213
	v_mul_f32_e32 v230, v230, v213
	v_mul_f32_e32 v231, v231, v213
	v_mul_f32_e32 v232, v232, v213
	v_mul_f32_e32 v233, v233, v213
	v_mul_f32_e32 v234, v234, v213
	v_mul_f32_e32 v235, v235, v213
	v_mul_f32_e32 v236, v236, v213
	v_mul_f32_e32 v237, v237, v213
	v_mul_f32_e32 v238, v238, v213
	v_mul_f32_e32 v239, v239, v213
	v_mul_f32_e32 v240, v240, v213
	v_mul_f32_e32 v241, v241, v213
	v_mul_f32_e32 v242, v242, v213
	v_mul_f32_e32 v243, v243, v213
	v_mul_f32_e32 v244, v244, v213
	v_mul_f32_e32 v245, v245, v213
	v_fma_f32 v214, v214, v112, v144
	v_fma_f32 v215, v215, v113, v145
	v_fma_f32 v216, v216, v114, v146
	v_fma_f32 v217, v217, v115, v147
	v_fma_f32 v218, v218, v116, v148
	v_fma_f32 v219, v219, v117, v149
	v_fma_f32 v220, v220, v118, v150
	v_fma_f32 v221, v221, v119, v151
	v_fma_f32 v222, v222, v120, v152
	v_fma_f32 v223, v223, v121, v153
	v_fma_f32 v224, v224, v122, v154
	v_fma_f32 v225, v225, v123, v155
	v_fma_f32 v226, v226, v124, v156
	v_fma_f32 v227, v227, v125, v157
	v_fma_f32 v228, v228, v126, v158
	v_fma_f32 v229, v229, v127, v159
	v_fma_f32 v230, v230, v128, v160
	v_fma_f32 v231, v231, v129, v161
	v_fma_f32 v232, v232, v130, v162
	v_fma_f32 v233, v233, v131, v163
	v_fma_f32 v234, v234, v132, v164
	v_fma_f32 v235, v235, v133, v165
	v_fma_f32 v236, v236, v134, v166
	v_fma_f32 v237, v237, v135, v167
	v_fma_f32 v238, v238, v136, v168
	v_fma_f32 v239, v239, v137, v169
	v_fma_f32 v240, v240, v138, v170
	v_fma_f32 v241, v241, v139, v171
	v_fma_f32 v242, v242, v140, v172
	v_fma_f32 v243, v243, v141, v173
	v_fma_f32 v244, v244, v142, v174
	v_fma_f32 v245, v245, v143, v175
	global_store_dwordx4 v[246:247], v[214:217], off
	global_store_dwordx4 v[246:247], v[218:221], off offset:1024
	global_store_dwordx4 v[246:247], v[222:225], off offset:2048
	global_store_dwordx4 v[246:247], v[226:229], off offset:3072
	global_store_dwordx4 v[248:249], v[230:233], off
	global_store_dwordx4 v[248:249], v[234:237], off offset:1024
	global_store_dwordx4 v[248:249], v[238:241], off offset:2048
	global_store_dwordx4 v[248:249], v[242:245], off offset:3072
	s_mov_b32 s24, 0xe000
	s_mov_b32 s25, 0
	v_lshl_add_u64 v[246:247], v[100:101], 0, s[24:25]
	s_mov_b32 s24, 0xf000
	v_lshl_add_u64 v[248:249], v[100:101], 0, s[24:25]
	global_load_dwordx4 v[214:217], v[246:247], off
	global_load_dwordx4 v[218:221], v[246:247], off offset:1024
	global_load_dwordx4 v[222:225], v[246:247], off offset:2048
	global_load_dwordx4 v[226:229], v[246:247], off offset:3072
	global_load_dwordx4 v[230:233], v[248:249], off
	global_load_dwordx4 v[234:237], v[248:249], off offset:1024
	global_load_dwordx4 v[238:241], v[248:249], off offset:2048
	global_load_dwordx4 v[242:245], v[248:249], off offset:3072
	s_waitcnt vmcnt(48)
; DI void ln_finish(const Params& p, float* __restrict__ pr, const float4 (&v)[8], int lane) {
;   float s = 0.f;
; #pragma unroll
;   for (int i = 0; i < 8; ++i) s += v[i].x + v[i].y + v[i].z + v[i].w;
; #pragma unroll
;   for (int o = 32; o >= 1; o >>= 1) s += __shfl_xor(s, o);
;   const float mu = s * (1.f / 2048.f);
;   float q = 0.f;
; #pragma unroll
;   for (int i = 0; i < 8; ++i) {
;     const float a = v[i].x - mu, b = v[i].y - mu, c = v[i].z - mu, d = v[i].w - mu;
;     q += a * a + b * b + c * c + d * d;
;   }
; #pragma unroll
;   for (int o = 32; o >= 1; o >>= 1) q += __shfl_xor(q, o);
;   const float rstd = rsqrtf(q * (1.f / 2048.f) + EPSV);
; #pragma unroll
;   for (int i = 0; i < 8; ++i) {
;     const int c0 = (i * 64 + lane) * 4;
;     const float4 g = *reinterpret_cast<const float4*>(p.ln_g + c0);
;     const float4 bb = *reinterpret_cast<const float4*>(p.ln_b + c0);
;     float4 o;
;     o.x = (v[i].x - mu) * rstd * g.x + bb.x;
;     o.y = (v[i].y - mu) * rstd * g.y + bb.y;
;     o.z = (v[i].z - mu) * rstd * g.z + bb.z;
;     o.w = (v[i].w - mu) * rstd * g.w + bb.w;
;     *reinterpret_cast<float4*>(pr + c0) = o;
;   }
	v_add_f32_e32 v208, v0, v4
	v_add_f32_e32 v209, v1, v5
	v_add_f32_e32 v210, v2, v6
	v_add_f32_e32 v211, v3, v7
	v_add_f32_e32 v208, v8, v208
	v_add_f32_e32 v209, v9, v209
	v_add_f32_e32 v210, v10, v210
	v_add_f32_e32 v211, v11, v211
	v_add_f32_e32 v208, v12, v208
	v_add_f32_e32 v209, v13, v209
	v_add_f32_e32 v210, v14, v210
	v_add_f32_e32 v211, v15, v211
	v_add_f32_e32 v208, v16, v208
	v_add_f32_e32 v209, v17, v209
	v_add_f32_e32 v210, v18, v210
	v_add_f32_e32 v211, v19, v211
	v_add_f32_e32 v208, v20, v208
	v_add_f32_e32 v209, v21, v209
	v_add_f32_e32 v210, v22, v210
	v_add_f32_e32 v211, v23, v211
	v_add_f32_e32 v208, v24, v208
	v_add_f32_e32 v209, v25, v209
	v_add_f32_e32 v210, v26, v210
	v_add_f32_e32 v211, v27, v211
	v_add_f32_e32 v208, v28, v208
	v_add_f32_e32 v209, v29, v209
	v_add_f32_e32 v210, v30, v210
	v_add_f32_e32 v211, v31, v211
	v_add_f32_e32 v208, v208, v209
	v_add_f32_e32 v210, v210, v211
	v_add_f32_e32 v208, v208, v210
	s_nop 1
	v_add_f32_dpp v208, v208, v208 quad_perm:[1,0,3,2] row_mask:0xf bank_mask:0xf
	s_nop 1
	v_add_f32_dpp v208, v208, v208 quad_perm:[2,3,0,1] row_mask:0xf bank_mask:0xf
	s_nop 1
	v_add_f32_dpp v208, v208, v208 row_half_mirror row_mask:0xf bank_mask:0xf
	s_nop 1
	v_add_f32_dpp v208, v208, v208 row_mirror row_mask:0xf bank_mask:0xf
	s_nop 1
	v_readlane_b32 s16, v208, 0
	v_readlane_b32 s17, v208, 16
	v_readlane_b32 s18, v208, 32
	v_readlane_b32 s19, v208, 48
	s_nop 1
	v_mov_b32_e32 v208, s16
	v_add_f32_e32 v208, s17, v208
	v_add_f32_e32 v208, s18, v208
	v_add_f32_e32 v208, s19, v208
	v_mul_f32_e32 v212, 0x3a000000, v208
	v_sub_f32_e32 v0, v0, v212
	v_sub_f32_e32 v1, v1, v212
	v_sub_f32_e32 v2, v2, v212
	v_sub_f32_e32 v3, v3, v212
	v_sub_f32_e32 v4, v4, v212
	v_sub_f32_e32 v5, v5, v212
	v_sub_f32_e32 v6, v6, v212
	v_sub_f32_e32 v7, v7, v212
	v_sub_f32_e32 v8, v8, v212
	v_sub_f32_e32 v9, v9, v212
	v_sub_f32_e32 v10, v10, v212
	v_sub_f32_e32 v11, v11, v212
	v_sub_f32_e32 v12, v12, v212
	v_sub_f32_e32 v13, v13, v212
	v_sub_f32_e32 v14, v14, v212
	v_sub_f32_e32 v15, v15, v212
	v_sub_f32_e32 v16, v16, v212
	v_sub_f32_e32 v17, v17, v212
	v_sub_f32_e32 v18, v18, v212
	v_sub_f32_e32 v19, v19, v212
	v_sub_f32_e32 v20, v20, v212
	v_sub_f32_e32 v21, v21, v212
	v_sub_f32_e32 v22, v22, v212
	v_sub_f32_e32 v23, v23, v212
	v_sub_f32_e32 v24, v24, v212
	v_sub_f32_e32 v25, v25, v212
	v_sub_f32_e32 v26, v26, v212
	v_sub_f32_e32 v27, v27, v212
	v_sub_f32_e32 v28, v28, v212
	v_sub_f32_e32 v29, v29, v212
	v_sub_f32_e32 v30, v30, v212
	v_sub_f32_e32 v31, v31, v212
	v_mul_f32_e32 v208, v0, v0
	v_mul_f32_e32 v209, v1, v1
	v_mul_f32_e32 v210, v2, v2
	v_mul_f32_e32 v211, v3, v3
	v_fmac_f32_e32 v208, v4, v4
	v_fmac_f32_e32 v209, v5, v5
	v_fmac_f32_e32 v210, v6, v6
	v_fmac_f32_e32 v211, v7, v7
	v_fmac_f32_e32 v208, v8, v8
	v_fmac_f32_e32 v209, v9, v9
	v_fmac_f32_e32 v210, v10, v10
	v_fmac_f32_e32 v211, v11, v11
	v_fmac_f32_e32 v208, v12, v12
	v_fmac_f32_e32 v209, v13, v13
	v_fmac_f32_e32 v210, v14, v14
	v_fmac_f32_e32 v211, v15, v15
	v_fmac_f32_e32 v208, v16, v16
	v_fmac_f32_e32 v209, v17, v17
	v_fmac_f32_e32 v210, v18, v18
	v_fmac_f32_e32 v211, v19, v19
	v_fmac_f32_e32 v208, v20, v20
	v_fmac_f32_e32 v209, v21, v21
	v_fmac_f32_e32 v210, v22, v22
	v_fmac_f32_e32 v211, v23, v23
	v_fmac_f32_e32 v208, v24, v24
	v_fmac_f32_e32 v209, v25, v25
	v_fmac_f32_e32 v210, v26, v26
	v_fmac_f32_e32 v211, v27, v27
	v_fmac_f32_e32 v208, v28, v28
	v_fmac_f32_e32 v209, v29, v29
	v_fmac_f32_e32 v210, v30, v30
	v_fmac_f32_e32 v211, v31, v31
	v_add_f32_e32 v208, v208, v209
	v_add_f32_e32 v210, v210, v211
	v_add_f32_e32 v208, v208, v210
	s_nop 1
	v_add_f32_dpp v208, v208, v208 quad_perm:[1,0,3,2] row_mask:0xf bank_mask:0xf
	s_nop 1
	v_add_f32_dpp v208, v208, v208 quad_perm:[2,3,0,1] row_mask:0xf bank_mask:0xf
	s_nop 1
	v_add_f32_dpp v208, v208, v208 row_half_mirror row_mask:0xf bank_mask:0xf
	s_nop 1
	v_add_f32_dpp v208, v208, v208 row_mirror row_mask:0xf bank_mask:0xf
	s_nop 1
	v_readlane_b32 s16, v208, 0
	v_readlane_b32 s17, v208, 16
	v_readlane_b32 s18, v208, 32
	v_readlane_b32 s19, v208, 48
	s_nop 1
	v_mov_b32_e32 v208, s16
	v_add_f32_e32 v208, s17, v208
	v_add_f32_e32 v208, s18, v208
	v_add_f32_e32 v208, s19, v208
	v_mov_b32_e32 v213, 0x3727c5ac
	v_fmac_f32_e32 v213, 0x3a000000, v208
	v_rsq_f32_e32 v213, v213
	s_nop 0
	v_mul_f32_e32 v0, v0, v213
	v_mul_f32_e32 v1, v1, v213
	v_mul_f32_e32 v2, v2, v213
	v_mul_f32_e32 v3, v3, v213
	v_mul_f32_e32 v4, v4, v213
	v_mul_f32_e32 v5, v5, v213
	v_mul_f32_e32 v6, v6, v213
	v_mul_f32_e32 v7, v7, v213
	v_mul_f32_e32 v8, v8, v213
	v_mul_f32_e32 v9, v9, v213
	v_mul_f32_e32 v10, v10, v213
	v_mul_f32_e32 v11, v11, v213
	v_mul_f32_e32 v12, v12, v213
	v_mul_f32_e32 v13, v13, v213
	v_mul_f32_e32 v14, v14, v213
	v_mul_f32_e32 v15, v15, v213
	v_mul_f32_e32 v16, v16, v213
	v_mul_f32_e32 v17, v17, v213
	v_mul_f32_e32 v18, v18, v213
	v_mul_f32_e32 v19, v19, v213
	v_mul_f32_e32 v20, v20, v213
	v_mul_f32_e32 v21, v21, v213
	v_mul_f32_e32 v22, v22, v213
	v_mul_f32_e32 v23, v23, v213
	v_mul_f32_e32 v24, v24, v213
	v_mul_f32_e32 v25, v25, v213
	v_mul_f32_e32 v26, v26, v213
	v_mul_f32_e32 v27, v27, v213
	v_mul_f32_e32 v28, v28, v213
	v_mul_f32_e32 v29, v29, v213
	v_mul_f32_e32 v30, v30, v213
	v_mul_f32_e32 v31, v31, v213
	v_fma_f32 v0, v0, v112, v144
	v_fma_f32 v1, v1, v113, v145
	v_fma_f32 v2, v2, v114, v146
	v_fma_f32 v3, v3, v115, v147
	v_fma_f32 v4, v4, v116, v148
	v_fma_f32 v5, v5, v117, v149
	v_fma_f32 v6, v6, v118, v150
	v_fma_f32 v7, v7, v119, v151
	v_fma_f32 v8, v8, v120, v152
	v_fma_f32 v9, v9, v121, v153
	v_fma_f32 v10, v10, v122, v154
	v_fma_f32 v11, v11, v123, v155
	v_fma_f32 v12, v12, v124, v156
	v_fma_f32 v13, v13, v125, v157
	v_fma_f32 v14, v14, v126, v158
	v_fma_f32 v15, v15, v127, v159
	v_fma_f32 v16, v16, v128, v160
	v_fma_f32 v17, v17, v129, v161
	v_fma_f32 v18, v18, v130, v162
	v_fma_f32 v19, v19, v131, v163
	v_fma_f32 v20, v20, v132, v164
	v_fma_f32 v21, v21, v133, v165
	v_fma_f32 v22, v22, v134, v166
	v_fma_f32 v23, v23, v135, v167
	v_fma_f32 v24, v24, v136, v168
	v_fma_f32 v25, v25, v137, v169
	v_fma_f32 v26, v26, v138, v170
	v_fma_f32 v27, v27, v139, v171
	v_fma_f32 v28, v28, v140, v172
	v_fma_f32 v29, v29, v141, v173
	v_fma_f32 v30, v30, v142, v174
	v_fma_f32 v31, v31, v143, v175
	global_store_dwordx4 v[88:89], v[0:3], off
	global_store_dwordx4 v[88:89], v[4:7], off offset:1024
	global_store_dwordx4 v[88:89], v[8:11], off offset:2048
	global_store_dwordx4 v[88:89], v[12:15], off offset:3072
	global_store_dwordx4 v[90:91], v[16:19], off
	global_store_dwordx4 v[90:91], v[20:23], off offset:1024
	global_store_dwordx4 v[90:91], v[24:27], off offset:2048
	global_store_dwordx4 v[90:91], v[28:31], off offset:3072
	s_waitcnt vmcnt(40)
; DI void ln_finish(const Params& p, float* __restrict__ pr, const float4 (&v)[8], int lane) {
;   float s = 0.f;
; #pragma unroll
;   for (int i = 0; i < 8; ++i) s += v[i].x + v[i].y + v[i].z + v[i].w;
; #pragma unroll
;   for (int o = 32; o >= 1; o >>= 1) s += __shfl_xor(s, o);
;   const float mu = s * (1.f / 2048.f);
;   float q = 0.f;
; #pragma unroll
;   for (int i = 0; i < 8; ++i) {
;     const float a = v[i].x - mu, b = v[i].y - mu, c = v[i].z - mu, d = v[i].w - mu;
;     q += a * a + b * b + c * c + d * d;
;   }
; #pragma unroll
;   for (int o = 32; o >= 1; o >>= 1) q += __shfl_xor(q, o);
;   const float rstd = rsqrtf(q * (1.f / 2048.f) + EPSV);
; #pragma unroll
;   for (int i = 0; i < 8; ++i) {
;     const int c0 = (i * 64 + lane) * 4;
;     const float4 g = *reinterpret_cast<const float4*>(p.ln_g + c0);
;     const float4 bb = *reinterpret_cast<const float4*>(p.ln_b + c0);
;     float4 o;
;     o.x = (v[i].x - mu) * rstd * g.x + bb.x;
;     o.y = (v[i].y - mu) * rstd * g.y + bb.y;
;     o.z = (v[i].z - mu) * rstd * g.z + bb.z;
;     o.w = (v[i].w - mu) * rstd * g.w + bb.w;
;     *reinterpret_cast<float4*>(pr + c0) = o;
;   }
	v_add_f32_e32 v208, v32, v36
	v_add_f32_e32 v209, v33, v37
	v_add_f32_e32 v210, v34, v38
	v_add_f32_e32 v211, v35, v39
	v_add_f32_e32 v208, v40, v208
	v_add_f32_e32 v209, v41, v209
	v_add_f32_e32 v210, v42, v210
	v_add_f32_e32 v211, v43, v211
	v_add_f32_e32 v208, v44, v208
	v_add_f32_e32 v209, v45, v209
	v_add_f32_e32 v210, v46, v210
	v_add_f32_e32 v211, v47, v211
	v_add_f32_e32 v208, v48, v208
	v_add_f32_e32 v209, v49, v209
	v_add_f32_e32 v210, v50, v210
	v_add_f32_e32 v211, v51, v211
	v_add_f32_e32 v208, v52, v208
	v_add_f32_e32 v209, v53, v209
	v_add_f32_e32 v210, v54, v210
	v_add_f32_e32 v211, v55, v211
	v_add_f32_e32 v208, v56, v208
	v_add_f32_e32 v209, v57, v209
	v_add_f32_e32 v210, v58, v210
	v_add_f32_e32 v211, v59, v211
	v_add_f32_e32 v208, v60, v208
	v_add_f32_e32 v209, v61, v209
	v_add_f32_e32 v210, v62, v210
	v_add_f32_e32 v211, v63, v211
	v_add_f32_e32 v208, v208, v209
	v_add_f32_e32 v210, v210, v211
	v_add_f32_e32 v208, v208, v210
	s_nop 1
	v_add_f32_dpp v208, v208, v208 quad_perm:[1,0,3,2] row_mask:0xf bank_mask:0xf
	s_nop 1
	v_add_f32_dpp v208, v208, v208 quad_perm:[2,3,0,1] row_mask:0xf bank_mask:0xf
	s_nop 1
	v_add_f32_dpp v208, v208, v208 row_half_mirror row_mask:0xf bank_mask:0xf
	s_nop 1
	v_add_f32_dpp v208, v208, v208 row_mirror row_mask:0xf bank_mask:0xf
	s_nop 1
	v_readlane_b32 s16, v208, 0
	v_readlane_b32 s17, v208, 16
	v_readlane_b32 s18, v208, 32
	v_readlane_b32 s19, v208, 48
	s_nop 1
	v_mov_b32_e32 v208, s16
	v_add_f32_e32 v208, s17, v208
	v_add_f32_e32 v208, s18, v208
	v_add_f32_e32 v208, s19, v208
	v_mul_f32_e32 v212, 0x3a000000, v208
	v_sub_f32_e32 v32, v32, v212
	v_sub_f32_e32 v33, v33, v212
	v_sub_f32_e32 v34, v34, v212
	v_sub_f32_e32 v35, v35, v212
	v_sub_f32_e32 v36, v36, v212
	v_sub_f32_e32 v37, v37, v212
	v_sub_f32_e32 v38, v38, v212
	v_sub_f32_e32 v39, v39, v212
	v_sub_f32_e32 v40, v40, v212
	v_sub_f32_e32 v41, v41, v212
	v_sub_f32_e32 v42, v42, v212
	v_sub_f32_e32 v43, v43, v212
	v_sub_f32_e32 v44, v44, v212
	v_sub_f32_e32 v45, v45, v212
	v_sub_f32_e32 v46, v46, v212
	v_sub_f32_e32 v47, v47, v212
	v_sub_f32_e32 v48, v48, v212
	v_sub_f32_e32 v49, v49, v212
	v_sub_f32_e32 v50, v50, v212
	v_sub_f32_e32 v51, v51, v212
	v_sub_f32_e32 v52, v52, v212
	v_sub_f32_e32 v53, v53, v212
	v_sub_f32_e32 v54, v54, v212
	v_sub_f32_e32 v55, v55, v212
	v_sub_f32_e32 v56, v56, v212
	v_sub_f32_e32 v57, v57, v212
	v_sub_f32_e32 v58, v58, v212
	v_sub_f32_e32 v59, v59, v212
	v_sub_f32_e32 v60, v60, v212
	v_sub_f32_e32 v61, v61, v212
	v_sub_f32_e32 v62, v62, v212
	v_sub_f32_e32 v63, v63, v212
	v_mul_f32_e32 v208, v32, v32
	v_mul_f32_e32 v209, v33, v33
	v_mul_f32_e32 v210, v34, v34
	v_mul_f32_e32 v211, v35, v35
	v_fmac_f32_e32 v208, v36, v36
	v_fmac_f32_e32 v209, v37, v37
	v_fmac_f32_e32 v210, v38, v38
	v_fmac_f32_e32 v211, v39, v39
	v_fmac_f32_e32 v208, v40, v40
	v_fmac_f32_e32 v209, v41, v41
	v_fmac_f32_e32 v210, v42, v42
	v_fmac_f32_e32 v211, v43, v43
	v_fmac_f32_e32 v208, v44, v44
	v_fmac_f32_e32 v209, v45, v45
	v_fmac_f32_e32 v210, v46, v46
	v_fmac_f32_e32 v211, v47, v47
	v_fmac_f32_e32 v208, v48, v48
	v_fmac_f32_e32 v209, v49, v49
	v_fmac_f32_e32 v210, v50, v50
	v_fmac_f32_e32 v211, v51, v51
	v_fmac_f32_e32 v208, v52, v52
	v_fmac_f32_e32 v209, v53, v53
	v_fmac_f32_e32 v210, v54, v54
	v_fmac_f32_e32 v211, v55, v55
	v_fmac_f32_e32 v208, v56, v56
	v_fmac_f32_e32 v209, v57, v57
	v_fmac_f32_e32 v210, v58, v58
	v_fmac_f32_e32 v211, v59, v59
	v_fmac_f32_e32 v208, v60, v60
	v_fmac_f32_e32 v209, v61, v61
	v_fmac_f32_e32 v210, v62, v62
	v_fmac_f32_e32 v211, v63, v63
	v_add_f32_e32 v208, v208, v209
	v_add_f32_e32 v210, v210, v211
	v_add_f32_e32 v208, v208, v210
	s_nop 1
	v_add_f32_dpp v208, v208, v208 quad_perm:[1,0,3,2] row_mask:0xf bank_mask:0xf
	s_nop 1
	v_add_f32_dpp v208, v208, v208 quad_perm:[2,3,0,1] row_mask:0xf bank_mask:0xf
	s_nop 1
	v_add_f32_dpp v208, v208, v208 row_half_mirror row_mask:0xf bank_mask:0xf
	s_nop 1
	v_add_f32_dpp v208, v208, v208 row_mirror row_mask:0xf bank_mask:0xf
	s_nop 1
	v_readlane_b32 s16, v208, 0
	v_readlane_b32 s17, v208, 16
	v_readlane_b32 s18, v208, 32
	v_readlane_b32 s19, v208, 48
	s_nop 1
	v_mov_b32_e32 v208, s16
	v_add_f32_e32 v208, s17, v208
	v_add_f32_e32 v208, s18, v208
	v_add_f32_e32 v208, s19, v208
	v_mov_b32_e32 v213, 0x3727c5ac
	v_fmac_f32_e32 v213, 0x3a000000, v208
	v_rsq_f32_e32 v213, v213
	s_nop 0
	v_mul_f32_e32 v32, v32, v213
	v_mul_f32_e32 v33, v33, v213
	v_mul_f32_e32 v34, v34, v213
	v_mul_f32_e32 v35, v35, v213
	v_mul_f32_e32 v36, v36, v213
	v_mul_f32_e32 v37, v37, v213
	v_mul_f32_e32 v38, v38, v213
	v_mul_f32_e32 v39, v39, v213
	v_mul_f32_e32 v40, v40, v213
	v_mul_f32_e32 v41, v41, v213
	v_mul_f32_e32 v42, v42, v213
	v_mul_f32_e32 v43, v43, v213
	v_mul_f32_e32 v44, v44, v213
	v_mul_f32_e32 v45, v45, v213
	v_mul_f32_e32 v46, v46, v213
	v_mul_f32_e32 v47, v47, v213
	v_mul_f32_e32 v48, v48, v213
	v_mul_f32_e32 v49, v49, v213
	v_mul_f32_e32 v50, v50, v213
	v_mul_f32_e32 v51, v51, v213
	v_mul_f32_e32 v52, v52, v213
	v_mul_f32_e32 v53, v53, v213
	v_mul_f32_e32 v54, v54, v213
	v_mul_f32_e32 v55, v55, v213
	v_mul_f32_e32 v56, v56, v213
	v_mul_f32_e32 v57, v57, v213
	v_mul_f32_e32 v58, v58, v213
	v_mul_f32_e32 v59, v59, v213
	v_mul_f32_e32 v60, v60, v213
	v_mul_f32_e32 v61, v61, v213
	v_mul_f32_e32 v62, v62, v213
	v_mul_f32_e32 v63, v63, v213
	v_fma_f32 v32, v32, v112, v144
	v_fma_f32 v33, v33, v113, v145
	v_fma_f32 v34, v34, v114, v146
	v_fma_f32 v35, v35, v115, v147
	v_fma_f32 v36, v36, v116, v148
	v_fma_f32 v37, v37, v117, v149
	v_fma_f32 v38, v38, v118, v150
	v_fma_f32 v39, v39, v119, v151
	v_fma_f32 v40, v40, v120, v152
	v_fma_f32 v41, v41, v121, v153
	v_fma_f32 v42, v42, v122, v154
	v_fma_f32 v43, v43, v123, v155
	v_fma_f32 v44, v44, v124, v156
	v_fma_f32 v45, v45, v125, v157
	v_fma_f32 v46, v46, v126, v158
	v_fma_f32 v47, v47, v127, v159
	v_fma_f32 v48, v48, v128, v160
	v_fma_f32 v49, v49, v129, v161
	v_fma_f32 v50, v50, v130, v162
	v_fma_f32 v51, v51, v131, v163
	v_fma_f32 v52, v52, v132, v164
	v_fma_f32 v53, v53, v133, v165
	v_fma_f32 v54, v54, v134, v166
	v_fma_f32 v55, v55, v135, v167
	v_fma_f32 v56, v56, v136, v168
	v_fma_f32 v57, v57, v137, v169
	v_fma_f32 v58, v58, v138, v170
	v_fma_f32 v59, v59, v139, v171
	v_fma_f32 v60, v60, v140, v172
	v_fma_f32 v61, v61, v141, v173
	v_fma_f32 v62, v62, v142, v174
	v_fma_f32 v63, v63, v143, v175
	global_store_dwordx4 v[92:93], v[32:35], off
	global_store_dwordx4 v[92:93], v[36:39], off offset:1024
	global_store_dwordx4 v[92:93], v[40:43], off offset:2048
	global_store_dwordx4 v[92:93], v[44:47], off offset:3072
	global_store_dwordx4 v[94:95], v[48:51], off
	global_store_dwordx4 v[94:95], v[52:55], off offset:1024
	global_store_dwordx4 v[94:95], v[56:59], off offset:2048
	global_store_dwordx4 v[94:95], v[60:63], off offset:3072
	s_waitcnt vmcnt(32)
; DI void ln_finish(const Params& p, float* __restrict__ pr, const float4 (&v)[8], int lane) {
;   float s = 0.f;
; #pragma unroll
;   for (int i = 0; i < 8; ++i) s += v[i].x + v[i].y + v[i].z + v[i].w;
; #pragma unroll
;   for (int o = 32; o >= 1; o >>= 1) s += __shfl_xor(s, o);
;   const float mu = s * (1.f / 2048.f);
;   float q = 0.f;
; #pragma unroll
;   for (int i = 0; i < 8; ++i) {
;     const float a = v[i].x - mu, b = v[i].y - mu, c = v[i].z - mu, d = v[i].w - mu;
;     q += a * a + b * b + c * c + d * d;
;   }
; #pragma unroll
;   for (int o = 32; o >= 1; o >>= 1) q += __shfl_xor(q, o);
;   const float rstd = rsqrtf(q * (1.f / 2048.f) + EPSV);
; #pragma unroll
;   for (int i = 0; i < 8; ++i) {
;     const int c0 = (i * 64 + lane) * 4;
;     const float4 g = *reinterpret_cast<const float4*>(p.ln_g + c0);
;     const float4 bb = *reinterpret_cast<const float4*>(p.ln_b + c0);
;     float4 o;
;     o.x = (v[i].x - mu) * rstd * g.x + bb.x;
;     o.y = (v[i].y - mu) * rstd * g.y + bb.y;
;     o.z = (v[i].z - mu) * rstd * g.z + bb.z;
;     o.w = (v[i].w - mu) * rstd * g.w + bb.w;
;     *reinterpret_cast<float4*>(pr + c0) = o;
;   }
	v_add_f32_e32 v208, v176, v180
	v_add_f32_e32 v209, v177, v181
	v_add_f32_e32 v210, v178, v182
	v_add_f32_e32 v211, v179, v183
	v_add_f32_e32 v208, v184, v208
	v_add_f32_e32 v209, v185, v209
	v_add_f32_e32 v210, v186, v210
	v_add_f32_e32 v211, v187, v211
	v_add_f32_e32 v208, v188, v208
	v_add_f32_e32 v209, v189, v209
	v_add_f32_e32 v210, v190, v210
	v_add_f32_e32 v211, v191, v211
	v_add_f32_e32 v208, v192, v208
	v_add_f32_e32 v209, v193, v209
	v_add_f32_e32 v210, v194, v210
	v_add_f32_e32 v211, v195, v211
	v_add_f32_e32 v208, v196, v208
	v_add_f32_e32 v209, v197, v209
	v_add_f32_e32 v210, v198, v210
	v_add_f32_e32 v211, v199, v211
	v_add_f32_e32 v208, v200, v208
	v_add_f32_e32 v209, v201, v209
	v_add_f32_e32 v210, v202, v210
	v_add_f32_e32 v211, v203, v211
	v_add_f32_e32 v208, v204, v208
	v_add_f32_e32 v209, v205, v209
	v_add_f32_e32 v210, v206, v210
	v_add_f32_e32 v211, v207, v211
	v_add_f32_e32 v208, v208, v209
	v_add_f32_e32 v210, v210, v211
	v_add_f32_e32 v208, v208, v210
	s_nop 1
	v_add_f32_dpp v208, v208, v208 quad_perm:[1,0,3,2] row_mask:0xf bank_mask:0xf
	s_nop 1
	v_add_f32_dpp v208, v208, v208 quad_perm:[2,3,0,1] row_mask:0xf bank_mask:0xf
	s_nop 1
	v_add_f32_dpp v208, v208, v208 row_half_mirror row_mask:0xf bank_mask:0xf
	s_nop 1
	v_add_f32_dpp v208, v208, v208 row_mirror row_mask:0xf bank_mask:0xf
	s_nop 1
	v_readlane_b32 s16, v208, 0
	v_readlane_b32 s17, v208, 16
	v_readlane_b32 s18, v208, 32
	v_readlane_b32 s19, v208, 48
	s_nop 1
	v_mov_b32_e32 v208, s16
	v_add_f32_e32 v208, s17, v208
	v_add_f32_e32 v208, s18, v208
	v_add_f32_e32 v208, s19, v208
	v_mul_f32_e32 v212, 0x3a000000, v208
	v_sub_f32_e32 v176, v176, v212
	v_sub_f32_e32 v177, v177, v212
	v_sub_f32_e32 v178, v178, v212
	v_sub_f32_e32 v179, v179, v212
	v_sub_f32_e32 v180, v180, v212
	v_sub_f32_e32 v181, v181, v212
	v_sub_f32_e32 v182, v182, v212
	v_sub_f32_e32 v183, v183, v212
	v_sub_f32_e32 v184, v184, v212
	v_sub_f32_e32 v185, v185, v212
	v_sub_f32_e32 v186, v186, v212
	v_sub_f32_e32 v187, v187, v212
	v_sub_f32_e32 v188, v188, v212
	v_sub_f32_e32 v189, v189, v212
	v_sub_f32_e32 v190, v190, v212
	v_sub_f32_e32 v191, v191, v212
	v_sub_f32_e32 v192, v192, v212
	v_sub_f32_e32 v193, v193, v212
	v_sub_f32_e32 v194, v194, v212
	v_sub_f32_e32 v195, v195, v212
	v_sub_f32_e32 v196, v196, v212
	v_sub_f32_e32 v197, v197, v212
	v_sub_f32_e32 v198, v198, v212
	v_sub_f32_e32 v199, v199, v212
	v_sub_f32_e32 v200, v200, v212
	v_sub_f32_e32 v201, v201, v212
	v_sub_f32_e32 v202, v202, v212
	v_sub_f32_e32 v203, v203, v212
	v_sub_f32_e32 v204, v204, v212
	v_sub_f32_e32 v205, v205, v212
	v_sub_f32_e32 v206, v206, v212
	v_sub_f32_e32 v207, v207, v212
	v_mul_f32_e32 v208, v176, v176
	v_mul_f32_e32 v209, v177, v177
	v_mul_f32_e32 v210, v178, v178
	v_mul_f32_e32 v211, v179, v179
	v_fmac_f32_e32 v208, v180, v180
	v_fmac_f32_e32 v209, v181, v181
	v_fmac_f32_e32 v210, v182, v182
	v_fmac_f32_e32 v211, v183, v183
	v_fmac_f32_e32 v208, v184, v184
	v_fmac_f32_e32 v209, v185, v185
	v_fmac_f32_e32 v210, v186, v186
	v_fmac_f32_e32 v211, v187, v187
	v_fmac_f32_e32 v208, v188, v188
	v_fmac_f32_e32 v209, v189, v189
	v_fmac_f32_e32 v210, v190, v190
	v_fmac_f32_e32 v211, v191, v191
	v_fmac_f32_e32 v208, v192, v192
	v_fmac_f32_e32 v209, v193, v193
	v_fmac_f32_e32 v210, v194, v194
	v_fmac_f32_e32 v211, v195, v195
	v_fmac_f32_e32 v208, v196, v196
	v_fmac_f32_e32 v209, v197, v197
	v_fmac_f32_e32 v210, v198, v198
	v_fmac_f32_e32 v211, v199, v199
	v_fmac_f32_e32 v208, v200, v200
	v_fmac_f32_e32 v209, v201, v201
	v_fmac_f32_e32 v210, v202, v202
	v_fmac_f32_e32 v211, v203, v203
	v_fmac_f32_e32 v208, v204, v204
	v_fmac_f32_e32 v209, v205, v205
	v_fmac_f32_e32 v210, v206, v206
	v_fmac_f32_e32 v211, v207, v207
	v_add_f32_e32 v208, v208, v209
	v_add_f32_e32 v210, v210, v211
	v_add_f32_e32 v208, v208, v210
	s_nop 1
	v_add_f32_dpp v208, v208, v208 quad_perm:[1,0,3,2] row_mask:0xf bank_mask:0xf
	s_nop 1
	v_add_f32_dpp v208, v208, v208 quad_perm:[2,3,0,1] row_mask:0xf bank_mask:0xf
	s_nop 1
	v_add_f32_dpp v208, v208, v208 row_half_mirror row_mask:0xf bank_mask:0xf
	s_nop 1
	v_add_f32_dpp v208, v208, v208 row_mirror row_mask:0xf bank_mask:0xf
	s_nop 1
	v_readlane_b32 s16, v208, 0
	v_readlane_b32 s17, v208, 16
	v_readlane_b32 s18, v208, 32
	v_readlane_b32 s19, v208, 48
	s_nop 1
	v_mov_b32_e32 v208, s16
	v_add_f32_e32 v208, s17, v208
	v_add_f32_e32 v208, s18, v208
	v_add_f32_e32 v208, s19, v208
	v_mov_b32_e32 v213, 0x3727c5ac
	v_fmac_f32_e32 v213, 0x3a000000, v208
	v_rsq_f32_e32 v213, v213
	s_nop 0
	v_mul_f32_e32 v176, v176, v213
	v_mul_f32_e32 v177, v177, v213
	v_mul_f32_e32 v178, v178, v213
	v_mul_f32_e32 v179, v179, v213
	v_mul_f32_e32 v180, v180, v213
	v_mul_f32_e32 v181, v181, v213
	v_mul_f32_e32 v182, v182, v213
	v_mul_f32_e32 v183, v183, v213
	v_mul_f32_e32 v184, v184, v213
	v_mul_f32_e32 v185, v185, v213
	v_mul_f32_e32 v186, v186, v213
	v_mul_f32_e32 v187, v187, v213
	v_mul_f32_e32 v188, v188, v213
	v_mul_f32_e32 v189, v189, v213
	v_mul_f32_e32 v190, v190, v213
	v_mul_f32_e32 v191, v191, v213
	v_mul_f32_e32 v192, v192, v213
	v_mul_f32_e32 v193, v193, v213
	v_mul_f32_e32 v194, v194, v213
	v_mul_f32_e32 v195, v195, v213
	v_mul_f32_e32 v196, v196, v213
	v_mul_f32_e32 v197, v197, v213
	v_mul_f32_e32 v198, v198, v213
	v_mul_f32_e32 v199, v199, v213
	v_mul_f32_e32 v200, v200, v213
	v_mul_f32_e32 v201, v201, v213
	v_mul_f32_e32 v202, v202, v213
	v_mul_f32_e32 v203, v203, v213
	v_mul_f32_e32 v204, v204, v213
	v_mul_f32_e32 v205, v205, v213
	v_mul_f32_e32 v206, v206, v213
	v_mul_f32_e32 v207, v207, v213
	v_fma_f32 v176, v176, v112, v144
	v_fma_f32 v177, v177, v113, v145
	v_fma_f32 v178, v178, v114, v146
	v_fma_f32 v179, v179, v115, v147
; DI void ln_finish(const Params& p, float* __restrict__ pr, const float4 (&v)[8], int lane) {
;   float s = 0.f;
; #pragma unroll
;   for (int i = 0; i < 8; ++i) s += v[i].x + v[i].y + v[i].z + v[i].w;
; #pragma unroll
;   for (int o = 32; o >= 1; o >>= 1) s += __shfl_xor(s, o);
;   const float mu = s * (1.f / 2048.f);
;   float q = 0.f;
; #pragma unroll
;   for (int i = 0; i < 8; ++i) {
;     const float a = v[i].x - mu, b = v[i].y - mu, c = v[i].z - mu, d = v[i].w - mu;
;     q += a * a + b * b + c * c + d * d;
;   }
; #pragma unroll
;   for (int o = 32; o >= 1; o >>= 1) q += __shfl_xor(q, o);
;   const float rstd = rsqrtf(q * (1.f / 2048.f) + EPSV);
; #pragma unroll
;   for (int i = 0; i < 8; ++i) {
;     const int c0 = (i * 64 + lane) * 4;
;     const float4 g = *reinterpret_cast<const float4*>(p.ln_g + c0);
;     const float4 bb = *reinterpret_cast<const float4*>(p.ln_b + c0);
;     float4 o;
;     o.x = (v[i].x - mu) * rstd * g.x + bb.x;
;     o.y = (v[i].y - mu) * rstd * g.y + bb.y;
;     o.z = (v[i].z - mu) * rstd * g.z + bb.z;
;     o.w = (v[i].w - mu) * rstd * g.w + bb.w;
;     *reinterpret_cast<float4*>(pr + c0) = o;
;   }
	v_fma_f32 v180, v180, v116, v148
	v_fma_f32 v181, v181, v117, v149
	v_fma_f32 v182, v182, v118, v150
	v_fma_f32 v183, v183, v119, v151
	v_fma_f32 v184, v184, v120, v152
	v_fma_f32 v185, v185, v121, v153
	v_fma_f32 v186, v186, v122, v154
	v_fma_f32 v187, v187, v123, v155
	v_fma_f32 v188, v188, v124, v156
	v_fma_f32 v189, v189, v125, v157
	v_fma_f32 v190, v190, v126, v158
	v_fma_f32 v191, v191, v127, v159
	v_fma_f32 v192, v192, v128, v160
	v_fma_f32 v193, v193, v129, v161
	v_fma_f32 v194, v194, v130, v162
	v_fma_f32 v195, v195, v131, v163
	v_fma_f32 v196, v196, v132, v164
	v_fma_f32 v197, v197, v133, v165
	v_fma_f32 v198, v198, v134, v166
	v_fma_f32 v199, v199, v135, v167
	v_fma_f32 v200, v200, v136, v168
	v_fma_f32 v201, v201, v137, v169
	v_fma_f32 v202, v202, v138, v170
	v_fma_f32 v203, v203, v139, v171
	v_fma_f32 v204, v204, v140, v172
	v_fma_f32 v205, v205, v141, v173
	v_fma_f32 v206, v206, v142, v174
	v_fma_f32 v207, v207, v143, v175
	global_store_dwordx4 v[96:97], v[176:179], off
	global_store_dwordx4 v[96:97], v[180:183], off offset:1024
	global_store_dwordx4 v[96:97], v[184:187], off offset:2048
	global_store_dwordx4 v[96:97], v[188:191], off offset:3072
	global_store_dwordx4 v[98:99], v[192:195], off
	global_store_dwordx4 v[98:99], v[196:199], off offset:1024
	global_store_dwordx4 v[98:99], v[200:203], off offset:2048
	global_store_dwordx4 v[98:99], v[204:207], off offset:3072
	s_waitcnt vmcnt(24)
	v_add_f32_e32 v208, v214, v218
	v_add_f32_e32 v209, v215, v219
	v_add_f32_e32 v210, v216, v220
	v_add_f32_e32 v211, v217, v221
	v_add_f32_e32 v208, v222, v208
	v_add_f32_e32 v209, v223, v209
	v_add_f32_e32 v210, v224, v210
	v_add_f32_e32 v211, v225, v211
	v_add_f32_e32 v208, v226, v208
	v_add_f32_e32 v209, v227, v209
	v_add_f32_e32 v210, v228, v210
	v_add_f32_e32 v211, v229, v211
	v_add_f32_e32 v208, v230, v208
	v_add_f32_e32 v209, v231, v209
	v_add_f32_e32 v210, v232, v210
	v_add_f32_e32 v211, v233, v211
	v_add_f32_e32 v208, v234, v208
	v_add_f32_e32 v209, v235, v209
	v_add_f32_e32 v210, v236, v210
	v_add_f32_e32 v211, v237, v211
	v_add_f32_e32 v208, v238, v208
	v_add_f32_e32 v209, v239, v209
	v_add_f32_e32 v210, v240, v210
	v_add_f32_e32 v211, v241, v211
	v_add_f32_e32 v208, v242, v208
	v_add_f32_e32 v209, v243, v209
	v_add_f32_e32 v210, v244, v210
	v_add_f32_e32 v211, v245, v211
	v_add_f32_e32 v208, v208, v209
	v_add_f32_e32 v210, v210, v211
	v_add_f32_e32 v208, v208, v210
	s_nop 1
	v_add_f32_dpp v208, v208, v208 quad_perm:[1,0,3,2] row_mask:0xf bank_mask:0xf
	s_nop 1
	v_add_f32_dpp v208, v208, v208 quad_perm:[2,3,0,1] row_mask:0xf bank_mask:0xf
	s_nop 1
	v_add_f32_dpp v208, v208, v208 row_half_mirror row_mask:0xf bank_mask:0xf
	s_nop 1
	v_add_f32_dpp v208, v208, v208 row_mirror row_mask:0xf bank_mask:0xf
	s_nop 1
	v_readlane_b32 s16, v208, 0
	v_readlane_b32 s17, v208, 16
	v_readlane_b32 s18, v208, 32
	v_readlane_b32 s19, v208, 48
	s_nop 1
	v_mov_b32_e32 v208, s16
	v_add_f32_e32 v208, s17, v208
	v_add_f32_e32 v208, s18, v208
	v_add_f32_e32 v208, s19, v208
	v_mul_f32_e32 v212, 0x3a000000, v208
	v_sub_f32_e32 v214, v214, v212
	v_sub_f32_e32 v215, v215, v212
	v_sub_f32_e32 v216, v216, v212
	v_sub_f32_e32 v217, v217, v212
	v_sub_f32_e32 v218, v218, v212
	v_sub_f32_e32 v219, v219, v212
	v_sub_f32_e32 v220, v220, v212
	v_sub_f32_e32 v221, v221, v212
	v_sub_f32_e32 v222, v222, v212
	v_sub_f32_e32 v223, v223, v212
	v_sub_f32_e32 v224, v224, v212
	v_sub_f32_e32 v225, v225, v212
	v_sub_f32_e32 v226, v226, v212
	v_sub_f32_e32 v227, v227, v212
	v_sub_f32_e32 v228, v228, v212
	v_sub_f32_e32 v229, v229, v212
	v_sub_f32_e32 v230, v230, v212
	v_sub_f32_e32 v231, v231, v212
	v_sub_f32_e32 v232, v232, v212
	v_sub_f32_e32 v233, v233, v212
	v_sub_f32_e32 v234, v234, v212
	v_sub_f32_e32 v235, v235, v212
	v_sub_f32_e32 v236, v236, v212
	v_sub_f32_e32 v237, v237, v212
	v_sub_f32_e32 v238, v238, v212
	v_sub_f32_e32 v239, v239, v212
	v_sub_f32_e32 v240, v240, v212
	v_sub_f32_e32 v241, v241, v212
	v_sub_f32_e32 v242, v242, v212
	v_sub_f32_e32 v243, v243, v212
	v_sub_f32_e32 v244, v244, v212
	v_sub_f32_e32 v245, v245, v212
	v_mul_f32_e32 v208, v214, v214
	v_mul_f32_e32 v209, v215, v215
	v_mul_f32_e32 v210, v216, v216
	v_mul_f32_e32 v211, v217, v217
	v_fmac_f32_e32 v208, v218, v218
	v_fmac_f32_e32 v209, v219, v219
; DI void ln_finish(const Params& p, float* __restrict__ pr, const float4 (&v)[8], int lane) {
;   float s = 0.f;
; #pragma unroll
;   for (int i = 0; i < 8; ++i) s += v[i].x + v[i].y + v[i].z + v[i].w;
; #pragma unroll
;   for (int o = 32; o >= 1; o >>= 1) s += __shfl_xor(s, o);
;   const float mu = s * (1.f / 2048.f);
;   float q = 0.f;
; #pragma unroll
;   for (int i = 0; i < 8; ++i) {
;     const float a = v[i].x - mu, b = v[i].y - mu, c = v[i].z - mu, d = v[i].w - mu;
;     q += a * a + b * b + c * c + d * d;
;   }
; #pragma unroll
;   for (int o = 32; o >= 1; o >>= 1) q += __shfl_xor(q, o);
;   const float rstd = rsqrtf(q * (1.f / 2048.f) + EPSV);
; #pragma unroll
;   for (int i = 0; i < 8; ++i) {
;     const int c0 = (i * 64 + lane) * 4;
;     const float4 g = *reinterpret_cast<const float4*>(p.ln_g + c0);
;     const float4 bb = *reinterpret_cast<const float4*>(p.ln_b + c0);
;     float4 o;
;     o.x = (v[i].x - mu) * rstd * g.x + bb.x;
;     o.y = (v[i].y - mu) * rstd * g.y + bb.y;
;     o.z = (v[i].z - mu) * rstd * g.z + bb.z;
;     o.w = (v[i].w - mu) * rstd * g.w + bb.w;
;     *reinterpret_cast<float4*>(pr + c0) = o;
;   }
	v_fmac_f32_e32 v210, v220, v220
	v_fmac_f32_e32 v211, v221, v221
	v_fmac_f32_e32 v208, v222, v222
	v_fmac_f32_e32 v209, v223, v223
	v_fmac_f32_e32 v210, v224, v224
	v_fmac_f32_e32 v211, v225, v225
	v_fmac_f32_e32 v208, v226, v226
	v_fmac_f32_e32 v209, v227, v227
	v_fmac_f32_e32 v210, v228, v228
	v_fmac_f32_e32 v211, v229, v229
	v_fmac_f32_e32 v208, v230, v230
	v_fmac_f32_e32 v209, v231, v231
	v_fmac_f32_e32 v210, v232, v232
	v_fmac_f32_e32 v211, v233, v233
	v_fmac_f32_e32 v208, v234, v234
	v_fmac_f32_e32 v209, v235, v235
	v_fmac_f32_e32 v210, v236, v236
	v_fmac_f32_e32 v211, v237, v237
	v_fmac_f32_e32 v208, v238, v238
	v_fmac_f32_e32 v209, v239, v239
	v_fmac_f32_e32 v210, v240, v240
	v_fmac_f32_e32 v211, v241, v241
	v_fmac_f32_e32 v208, v242, v242
	v_fmac_f32_e32 v209, v243, v243
	v_fmac_f32_e32 v210, v244, v244
	v_fmac_f32_e32 v211, v245, v245
	v_add_f32_e32 v208, v208, v209
	v_add_f32_e32 v210, v210, v211
	v_add_f32_e32 v208, v208, v210
	s_nop 1
	v_add_f32_dpp v208, v208, v208 quad_perm:[1,0,3,2] row_mask:0xf bank_mask:0xf
	s_nop 1
	v_add_f32_dpp v208, v208, v208 quad_perm:[2,3,0,1] row_mask:0xf bank_mask:0xf
	s_nop 1
	v_add_f32_dpp v208, v208, v208 row_half_mirror row_mask:0xf bank_mask:0xf
	s_nop 1
	v_add_f32_dpp v208, v208, v208 row_mirror row_mask:0xf bank_mask:0xf
	s_nop 1
	v_readlane_b32 s16, v208, 0
	v_readlane_b32 s17, v208, 16
	v_readlane_b32 s18, v208, 32
	v_readlane_b32 s19, v208, 48
	s_nop 1
	v_mov_b32_e32 v208, s16
	v_add_f32_e32 v208, s17, v208
	v_add_f32_e32 v208, s18, v208
	v_add_f32_e32 v208, s19, v208
	v_mov_b32_e32 v213, 0x3727c5ac
	v_fmac_f32_e32 v213, 0x3a000000, v208
	v_rsq_f32_e32 v213, v213
	s_nop 0
	v_mul_f32_e32 v214, v214, v213
	v_mul_f32_e32 v215, v215, v213
	v_mul_f32_e32 v216, v216, v213
	v_mul_f32_e32 v217, v217, v213
	v_mul_f32_e32 v218, v218, v213
	v_mul_f32_e32 v219, v219, v213
	v_mul_f32_e32 v220, v220, v213
	v_mul_f32_e32 v221, v221, v213
	v_mul_f32_e32 v222, v222, v213
	v_mul_f32_e32 v223, v223, v213
	v_mul_f32_e32 v224, v224, v213
	v_mul_f32_e32 v225, v225, v213
	v_mul_f32_e32 v226, v226, v213
	v_mul_f32_e32 v227, v227, v213
	v_mul_f32_e32 v228, v228, v213
	v_mul_f32_e32 v229, v229, v213
	v_mul_f32_e32 v230, v230, v213
	v_mul_f32_e32 v231, v231, v213
	v_mul_f32_e32 v232, v232, v213
	v_mul_f32_e32 v233, v233, v213
	v_mul_f32_e32 v234, v234, v213
	v_mul_f32_e32 v235, v235, v213
	v_mul_f32_e32 v236, v236, v213
	v_mul_f32_e32 v237, v237, v213
	v_mul_f32_e32 v238, v238, v213
	v_mul_f32_e32 v239, v239, v213
	v_mul_f32_e32 v240, v240, v213
	v_mul_f32_e32 v241, v241, v213
	v_mul_f32_e32 v242, v242, v213
	v_mul_f32_e32 v243, v243, v213
	v_mul_f32_e32 v244, v244, v213
	v_mul_f32_e32 v245, v245, v213
	v_fma_f32 v214, v214, v112, v144
	v_fma_f32 v215, v215, v113, v145
	v_fma_f32 v216, v216, v114, v146
	v_fma_f32 v217, v217, v115, v147
	v_fma_f32 v218, v218, v116, v148
	v_fma_f32 v219, v219, v117, v149
	v_fma_f32 v220, v220, v118, v150
	v_fma_f32 v221, v221, v119, v151
	v_fma_f32 v222, v222, v120, v152
	v_fma_f32 v223, v223, v121, v153
	v_fma_f32 v224, v224, v122, v154
	v_fma_f32 v225, v225, v123, v155
	v_fma_f32 v226, v226, v124, v156
	v_fma_f32 v227, v227, v125, v157
	v_fma_f32 v228, v228, v126, v158
	v_fma_f32 v229, v229, v127, v159
	v_fma_f32 v230, v230, v128, v160
	v_fma_f32 v231, v231, v129, v161
	v_fma_f32 v232, v232, v130, v162
	v_fma_f32 v233, v233, v131, v163
	v_fma_f32 v234, v234, v132, v164
	v_fma_f32 v235, v235, v133, v165
	v_fma_f32 v236, v236, v134, v166
	v_fma_f32 v237, v237, v135, v167
	v_fma_f32 v238, v238, v136, v168
	v_fma_f32 v239, v239, v137, v169
	v_fma_f32 v240, v240, v138, v170
	v_fma_f32 v241, v241, v139, v171
	v_fma_f32 v242, v242, v140, v172
	v_fma_f32 v243, v243, v141, v173
	v_fma_f32 v244, v244, v142, v174
	v_fma_f32 v245, v245, v143, v175
	global_store_dwordx4 v[246:247], v[214:217], off
	global_store_dwordx4 v[246:247], v[218:221], off offset:1024
	global_store_dwordx4 v[246:247], v[222:225], off offset:2048
	global_store_dwordx4 v[246:247], v[226:229], off offset:3072
	global_store_dwordx4 v[248:249], v[230:233], off
	global_store_dwordx4 v[248:249], v[234:237], off offset:1024
	global_store_dwordx4 v[248:249], v[238:241], off offset:2048
	global_store_dwordx4 v[248:249], v[242:245], off offset:3072
	s_mov_b64 s[4:5], 0
	s_branch .LBB0_659
